# in-projection epilogue regenerated: one running output pointer (a 64-bit add per row group), bf16 conversion in place on the accumulator quads, three straight-line variants (plain, silu*weight, sigmoi
# speedup vs baseline: 1.0024x; 1.0024x over previous
.LBB0_265:
	s_add_i32 s2, s78, 0xffffffbd
	s_cmpk_gt_i32 s78, 0x42
	s_cselect_b32 s8, 3, 0
	s_and_b64 s[6:7], s[6:7], exec
	s_cselect_b32 s6, 2, s8
	s_cmp_lt_u32 s2, -8
	s_cselect_b32 s2, s6, 1
	s_cmp_lg_u32 s2, 0
	s_cselect_b64 s[38:39], -1, 0
	s_cmp_eq_u32 s2, 3
	s_cselect_b64 s[6:7], -1, 0
	s_cmp_eq_u32 s2, 0
	s_cbranch_scc1 .Lepn0_m0
	s_and_b64 vcc, exec, s[6:7]
	s_cbranch_vccnz .Lepn0_m3
	v_readlane_b32 s8, v249, 43
	v_readlane_b32 s9, v249, 44
	v_lshl_or_b32 v154, s78, 8, v163
	v_ashrrev_i32_e32 v155, 31, v154
	v_mov_b64_e32 v[156:157], s[8:9]
	v_mad_i64_i32 v[156:157], s[8:9], v152, s76, v[156:157]
	v_lshl_add_u64 v[156:157], v[154:155], 1, v[156:157]
	s_lshl_b32 s98, s76, 4
	s_mov_b32 s99, 0
	s_mul_i32 s100, s76, 0x50
	s_mov_b32 s101, 0
	v_mov_b32_e32 v242, 0xbfb8aa3b
	s_waitcnt vmcnt(0)
	v_pk_mul_f32 v[234:235], v[66:67], v[242:243] op_sel_hi:[1,0]
	v_exp_f32_e32 v234, v234
	v_exp_f32_e32 v235, v235
	v_pk_mul_f32 v[236:237], v[68:69], v[242:243] op_sel_hi:[1,0]
	v_exp_f32_e32 v236, v236
	v_exp_f32_e32 v237, v237
	v_pk_mul_f32 v[238:239], v[70:71], v[242:243] op_sel_hi:[1,0]
	v_exp_f32_e32 v238, v238
	v_exp_f32_e32 v239, v239
	v_pk_mul_f32 v[240:241], v[72:73], v[242:243] op_sel_hi:[1,0]
	v_exp_f32_e32 v240, v240
	v_exp_f32_e32 v241, v241
	v_pk_add_f32 v[234:235], v[234:235], 1.0 op_sel_hi:[1,0]
	v_rcp_f32_e32 v234, v234
	v_rcp_f32_e32 v235, v235
	v_pk_add_f32 v[236:237], v[236:237], 1.0 op_sel_hi:[1,0]
	v_rcp_f32_e32 v236, v236
	v_rcp_f32_e32 v237, v237
	v_pk_add_f32 v[238:239], v[238:239], 1.0 op_sel_hi:[1,0]
	v_rcp_f32_e32 v238, v238
	v_rcp_f32_e32 v239, v239
	v_pk_add_f32 v[240:241], v[240:241], 1.0 op_sel_hi:[1,0]
	v_rcp_f32_e32 v240, v240
	v_rcp_f32_e32 v241, v241
	v_pk_mul_f32 v[66:67], v[66:67], v[234:235]
	v_pk_mul_f32 v[66:67], v[66:67], v[94:95]
	v_pk_mul_f32 v[68:69], v[68:69], v[236:237]
	v_pk_mul_f32 v[68:69], v[68:69], v[96:97]
	v_pk_mul_f32 v[70:71], v[70:71], v[238:239]
	v_pk_mul_f32 v[70:71], v[70:71], v[90:91]
	v_pk_mul_f32 v[72:73], v[72:73], v[240:241]
	v_pk_mul_f32 v[72:73], v[72:73], v[92:93]
	v_cvt_pk_bf16_f32 v70, v70, v71
	v_cvt_pk_bf16_f32 v71, v72, v73
	v_cvt_pk_bf16_f32 v72, v66, v67
	v_cvt_pk_bf16_f32 v73, v68, v69
	global_store_dwordx4 v[156:157], v[70:73], off nt
	v_pk_mul_f32 v[234:235], v[130:131], v[242:243] op_sel_hi:[1,0]
	v_exp_f32_e32 v234, v234
	v_exp_f32_e32 v235, v235
	v_pk_mul_f32 v[236:237], v[132:133], v[242:243] op_sel_hi:[1,0]
	v_exp_f32_e32 v236, v236
	v_exp_f32_e32 v237, v237
	v_pk_mul_f32 v[238:239], v[134:135], v[242:243] op_sel_hi:[1,0]
	v_exp_f32_e32 v238, v238
	v_exp_f32_e32 v239, v239
	v_pk_mul_f32 v[240:241], v[136:137], v[242:243] op_sel_hi:[1,0]
	v_exp_f32_e32 v240, v240
	v_exp_f32_e32 v241, v241
	v_pk_add_f32 v[234:235], v[234:235], 1.0 op_sel_hi:[1,0]
	v_rcp_f32_e32 v234, v234
	v_rcp_f32_e32 v235, v235
	v_pk_add_f32 v[236:237], v[236:237], 1.0 op_sel_hi:[1,0]
	v_rcp_f32_e32 v236, v236
	v_rcp_f32_e32 v237, v237
	v_pk_add_f32 v[238:239], v[238:239], 1.0 op_sel_hi:[1,0]
	v_rcp_f32_e32 v238, v238
	v_rcp_f32_e32 v239, v239
	v_pk_add_f32 v[240:241], v[240:241], 1.0 op_sel_hi:[1,0]
	v_rcp_f32_e32 v240, v240
	v_rcp_f32_e32 v241, v241
	v_pk_mul_f32 v[130:131], v[130:131], v[234:235]
	v_pk_mul_f32 v[130:131], v[130:131], v[94:95]
	v_pk_mul_f32 v[132:133], v[132:133], v[236:237]
	v_pk_mul_f32 v[132:133], v[132:133], v[96:97]
	v_pk_mul_f32 v[134:135], v[134:135], v[238:239]
	v_pk_mul_f32 v[134:135], v[134:135], v[90:91]
	v_pk_mul_f32 v[136:137], v[136:137], v[240:241]
	v_pk_mul_f32 v[136:137], v[136:137], v[92:93]
	v_cvt_pk_bf16_f32 v134, v134, v135
	v_cvt_pk_bf16_f32 v135, v136, v137
	v_cvt_pk_bf16_f32 v136, v130, v131
	v_cvt_pk_bf16_f32 v137, v132, v133
	global_store_dwordx4 v[156:157], v[134:137], off offset:256 nt
	v_lshl_add_u64 v[156:157], v[156:157], 0, s[98:99]
	v_pk_mul_f32 v[234:235], v[58:59], v[242:243] op_sel_hi:[1,0]
	v_exp_f32_e32 v234, v234
	v_exp_f32_e32 v235, v235
	v_pk_mul_f32 v[236:237], v[60:61], v[242:243] op_sel_hi:[1,0]
	v_exp_f32_e32 v236, v236
	v_exp_f32_e32 v237, v237
	v_pk_mul_f32 v[238:239], v[62:63], v[242:243] op_sel_hi:[1,0]
	v_exp_f32_e32 v238, v238
	v_exp_f32_e32 v239, v239
	v_pk_mul_f32 v[240:241], v[64:65], v[242:243] op_sel_hi:[1,0]
	v_exp_f32_e32 v240, v240
	v_exp_f32_e32 v241, v241
	v_pk_add_f32 v[234:235], v[234:235], 1.0 op_sel_hi:[1,0]
	v_rcp_f32_e32 v234, v234
	v_rcp_f32_e32 v235, v235
	v_pk_add_f32 v[236:237], v[236:237], 1.0 op_sel_hi:[1,0]
	v_rcp_f32_e32 v236, v236
	v_rcp_f32_e32 v237, v237
	v_pk_add_f32 v[238:239], v[238:239], 1.0 op_sel_hi:[1,0]
	v_rcp_f32_e32 v238, v238
	v_rcp_f32_e32 v239, v239
	v_pk_add_f32 v[240:241], v[240:241], 1.0 op_sel_hi:[1,0]
	v_rcp_f32_e32 v240, v240
	v_rcp_f32_e32 v241, v241
	v_pk_mul_f32 v[58:59], v[58:59], v[234:235]
	v_pk_mul_f32 v[58:59], v[58:59], v[94:95]
	v_pk_mul_f32 v[60:61], v[60:61], v[236:237]
	v_pk_mul_f32 v[60:61], v[60:61], v[96:97]
	v_pk_mul_f32 v[62:63], v[62:63], v[238:239]
	v_pk_mul_f32 v[62:63], v[62:63], v[90:91]
	v_pk_mul_f32 v[64:65], v[64:65], v[240:241]
	v_pk_mul_f32 v[64:65], v[64:65], v[92:93]
	v_cvt_pk_bf16_f32 v62, v62, v63
	v_cvt_pk_bf16_f32 v63, v64, v65
	v_cvt_pk_bf16_f32 v64, v58, v59
	v_cvt_pk_bf16_f32 v65, v60, v61
	global_store_dwordx4 v[156:157], v[62:65], off nt
	v_pk_mul_f32 v[234:235], v[122:123], v[242:243] op_sel_hi:[1,0]
	v_exp_f32_e32 v234, v234
	v_exp_f32_e32 v235, v235
	v_pk_mul_f32 v[236:237], v[124:125], v[242:243] op_sel_hi:[1,0]
	v_exp_f32_e32 v236, v236
	v_exp_f32_e32 v237, v237
	v_pk_mul_f32 v[238:239], v[126:127], v[242:243] op_sel_hi:[1,0]
	v_exp_f32_e32 v238, v238
	v_exp_f32_e32 v239, v239
	v_pk_mul_f32 v[240:241], v[128:129], v[242:243] op_sel_hi:[1,0]
	v_exp_f32_e32 v240, v240
	v_exp_f32_e32 v241, v241
	v_pk_add_f32 v[234:235], v[234:235], 1.0 op_sel_hi:[1,0]
	v_rcp_f32_e32 v234, v234
	v_rcp_f32_e32 v235, v235
	v_pk_add_f32 v[236:237], v[236:237], 1.0 op_sel_hi:[1,0]
	v_rcp_f32_e32 v236, v236
	v_rcp_f32_e32 v237, v237
	v_pk_add_f32 v[238:239], v[238:239], 1.0 op_sel_hi:[1,0]
	v_rcp_f32_e32 v238, v238
	v_rcp_f32_e32 v239, v239
	v_pk_add_f32 v[240:241], v[240:241], 1.0 op_sel_hi:[1,0]
	v_rcp_f32_e32 v240, v240
	v_rcp_f32_e32 v241, v241
	v_pk_mul_f32 v[122:123], v[122:123], v[234:235]
	v_pk_mul_f32 v[122:123], v[122:123], v[94:95]
	v_pk_mul_f32 v[124:125], v[124:125], v[236:237]
	v_pk_mul_f32 v[124:125], v[124:125], v[96:97]
	v_pk_mul_f32 v[126:127], v[126:127], v[238:239]
	v_pk_mul_f32 v[126:127], v[126:127], v[90:91]
	v_pk_mul_f32 v[128:129], v[128:129], v[240:241]
	v_pk_mul_f32 v[128:129], v[128:129], v[92:93]
	v_cvt_pk_bf16_f32 v126, v126, v127
	v_cvt_pk_bf16_f32 v127, v128, v129
	v_cvt_pk_bf16_f32 v128, v122, v123
	v_cvt_pk_bf16_f32 v129, v124, v125
	global_store_dwordx4 v[156:157], v[126:129], off offset:256 nt
	v_lshl_add_u64 v[156:157], v[156:157], 0, s[98:99]
	v_pk_mul_f32 v[234:235], v[50:51], v[242:243] op_sel_hi:[1,0]
	v_exp_f32_e32 v234, v234
	v_exp_f32_e32 v235, v235
	v_pk_mul_f32 v[236:237], v[52:53], v[242:243] op_sel_hi:[1,0]
	v_exp_f32_e32 v236, v236
	v_exp_f32_e32 v237, v237
	v_pk_mul_f32 v[238:239], v[54:55], v[242:243] op_sel_hi:[1,0]
	v_exp_f32_e32 v238, v238
	v_exp_f32_e32 v239, v239
	v_pk_mul_f32 v[240:241], v[56:57], v[242:243] op_sel_hi:[1,0]
	v_exp_f32_e32 v240, v240
	v_exp_f32_e32 v241, v241
	v_pk_add_f32 v[234:235], v[234:235], 1.0 op_sel_hi:[1,0]
	v_rcp_f32_e32 v234, v234
	v_rcp_f32_e32 v235, v235
	v_pk_add_f32 v[236:237], v[236:237], 1.0 op_sel_hi:[1,0]
	v_rcp_f32_e32 v236, v236
	v_rcp_f32_e32 v237, v237
	v_pk_add_f32 v[238:239], v[238:239], 1.0 op_sel_hi:[1,0]
	v_rcp_f32_e32 v238, v238
	v_rcp_f32_e32 v239, v239
	v_pk_add_f32 v[240:241], v[240:241], 1.0 op_sel_hi:[1,0]
	v_rcp_f32_e32 v240, v240
	v_rcp_f32_e32 v241, v241
	v_pk_mul_f32 v[50:51], v[50:51], v[234:235]
	v_pk_mul_f32 v[50:51], v[50:51], v[94:95]
	v_pk_mul_f32 v[52:53], v[52:53], v[236:237]
	v_pk_mul_f32 v[52:53], v[52:53], v[96:97]
	v_pk_mul_f32 v[54:55], v[54:55], v[238:239]
	v_pk_mul_f32 v[54:55], v[54:55], v[90:91]
	v_pk_mul_f32 v[56:57], v[56:57], v[240:241]
	v_pk_mul_f32 v[56:57], v[56:57], v[92:93]
	v_cvt_pk_bf16_f32 v54, v54, v55
	v_cvt_pk_bf16_f32 v55, v56, v57
	v_cvt_pk_bf16_f32 v56, v50, v51
	v_cvt_pk_bf16_f32 v57, v52, v53
	global_store_dwordx4 v[156:157], v[54:57], off nt
	v_pk_mul_f32 v[234:235], v[114:115], v[242:243] op_sel_hi:[1,0]
	v_exp_f32_e32 v234, v234
	v_exp_f32_e32 v235, v235
	v_pk_mul_f32 v[236:237], v[116:117], v[242:243] op_sel_hi:[1,0]
	v_exp_f32_e32 v236, v236
	v_exp_f32_e32 v237, v237
	v_pk_mul_f32 v[238:239], v[118:119], v[242:243] op_sel_hi:[1,0]
	v_exp_f32_e32 v238, v238
	v_exp_f32_e32 v239, v239
	v_pk_mul_f32 v[240:241], v[120:121], v[242:243] op_sel_hi:[1,0]
	v_exp_f32_e32 v240, v240
	v_exp_f32_e32 v241, v241
	v_pk_add_f32 v[234:235], v[234:235], 1.0 op_sel_hi:[1,0]
	v_rcp_f32_e32 v234, v234
	v_rcp_f32_e32 v235, v235
	v_pk_add_f32 v[236:237], v[236:237], 1.0 op_sel_hi:[1,0]
	v_rcp_f32_e32 v236, v236
	v_rcp_f32_e32 v237, v237
	v_pk_add_f32 v[238:239], v[238:239], 1.0 op_sel_hi:[1,0]
	v_rcp_f32_e32 v238, v238
	v_rcp_f32_e32 v239, v239
	v_pk_add_f32 v[240:241], v[240:241], 1.0 op_sel_hi:[1,0]
	v_rcp_f32_e32 v240, v240
	v_rcp_f32_e32 v241, v241
	v_pk_mul_f32 v[114:115], v[114:115], v[234:235]
	v_pk_mul_f32 v[114:115], v[114:115], v[94:95]
	v_pk_mul_f32 v[116:117], v[116:117], v[236:237]
	v_pk_mul_f32 v[116:117], v[116:117], v[96:97]
	v_pk_mul_f32 v[118:119], v[118:119], v[238:239]
	v_pk_mul_f32 v[118:119], v[118:119], v[90:91]
	v_pk_mul_f32 v[120:121], v[120:121], v[240:241]
	v_pk_mul_f32 v[120:121], v[120:121], v[92:93]
	v_cvt_pk_bf16_f32 v118, v118, v119
	v_cvt_pk_bf16_f32 v119, v120, v121
	v_cvt_pk_bf16_f32 v120, v114, v115
	v_cvt_pk_bf16_f32 v121, v116, v117
	global_store_dwordx4 v[156:157], v[118:121], off offset:256 nt
	v_lshl_add_u64 v[156:157], v[156:157], 0, s[98:99]
	v_pk_mul_f32 v[234:235], v[42:43], v[242:243] op_sel_hi:[1,0]
	v_exp_f32_e32 v234, v234
	v_exp_f32_e32 v235, v235
	v_pk_mul_f32 v[236:237], v[44:45], v[242:243] op_sel_hi:[1,0]
	v_exp_f32_e32 v236, v236
	v_exp_f32_e32 v237, v237
	v_pk_mul_f32 v[238:239], v[46:47], v[242:243] op_sel_hi:[1,0]
	v_exp_f32_e32 v238, v238
	v_exp_f32_e32 v239, v239
	v_pk_mul_f32 v[240:241], v[48:49], v[242:243] op_sel_hi:[1,0]
	v_exp_f32_e32 v240, v240
	v_exp_f32_e32 v241, v241
	v_pk_add_f32 v[234:235], v[234:235], 1.0 op_sel_hi:[1,0]
	v_rcp_f32_e32 v234, v234
	v_rcp_f32_e32 v235, v235
	v_pk_add_f32 v[236:237], v[236:237], 1.0 op_sel_hi:[1,0]
	v_rcp_f32_e32 v236, v236
	v_rcp_f32_e32 v237, v237
	v_pk_add_f32 v[238:239], v[238:239], 1.0 op_sel_hi:[1,0]
	v_rcp_f32_e32 v238, v238
	v_rcp_f32_e32 v239, v239
	v_pk_add_f32 v[240:241], v[240:241], 1.0 op_sel_hi:[1,0]
	v_rcp_f32_e32 v240, v240
	v_rcp_f32_e32 v241, v241
	v_pk_mul_f32 v[42:43], v[42:43], v[234:235]
	v_pk_mul_f32 v[42:43], v[42:43], v[94:95]
	v_pk_mul_f32 v[44:45], v[44:45], v[236:237]
	v_pk_mul_f32 v[44:45], v[44:45], v[96:97]
	v_pk_mul_f32 v[46:47], v[46:47], v[238:239]
	v_pk_mul_f32 v[46:47], v[46:47], v[90:91]
	v_pk_mul_f32 v[48:49], v[48:49], v[240:241]
	v_pk_mul_f32 v[48:49], v[48:49], v[92:93]
	v_cvt_pk_bf16_f32 v46, v46, v47
	v_cvt_pk_bf16_f32 v47, v48, v49
	v_cvt_pk_bf16_f32 v48, v42, v43
	v_cvt_pk_bf16_f32 v49, v44, v45
	global_store_dwordx4 v[156:157], v[46:49], off nt
	v_pk_mul_f32 v[234:235], v[106:107], v[242:243] op_sel_hi:[1,0]
	v_exp_f32_e32 v234, v234
	v_exp_f32_e32 v235, v235
	v_pk_mul_f32 v[236:237], v[108:109], v[242:243] op_sel_hi:[1,0]
	v_exp_f32_e32 v236, v236
	v_exp_f32_e32 v237, v237
	v_pk_mul_f32 v[238:239], v[110:111], v[242:243] op_sel_hi:[1,0]
	v_exp_f32_e32 v238, v238
	v_exp_f32_e32 v239, v239
	v_pk_mul_f32 v[240:241], v[112:113], v[242:243] op_sel_hi:[1,0]
	v_exp_f32_e32 v240, v240
	v_exp_f32_e32 v241, v241
	v_pk_add_f32 v[234:235], v[234:235], 1.0 op_sel_hi:[1,0]
	v_rcp_f32_e32 v234, v234
	v_rcp_f32_e32 v235, v235
	v_pk_add_f32 v[236:237], v[236:237], 1.0 op_sel_hi:[1,0]
	v_rcp_f32_e32 v236, v236
	v_rcp_f32_e32 v237, v237
	v_pk_add_f32 v[238:239], v[238:239], 1.0 op_sel_hi:[1,0]
	v_rcp_f32_e32 v238, v238
	v_rcp_f32_e32 v239, v239
	v_pk_add_f32 v[240:241], v[240:241], 1.0 op_sel_hi:[1,0]
	v_rcp_f32_e32 v240, v240
	v_rcp_f32_e32 v241, v241
	v_pk_mul_f32 v[106:107], v[106:107], v[234:235]
	v_pk_mul_f32 v[106:107], v[106:107], v[94:95]
	v_pk_mul_f32 v[108:109], v[108:109], v[236:237]
	v_pk_mul_f32 v[108:109], v[108:109], v[96:97]
	v_pk_mul_f32 v[110:111], v[110:111], v[238:239]
	v_pk_mul_f32 v[110:111], v[110:111], v[90:91]
	v_pk_mul_f32 v[112:113], v[112:113], v[240:241]
	v_pk_mul_f32 v[112:113], v[112:113], v[92:93]
	v_cvt_pk_bf16_f32 v110, v110, v111
	v_cvt_pk_bf16_f32 v111, v112, v113
	v_cvt_pk_bf16_f32 v112, v106, v107
	v_cvt_pk_bf16_f32 v113, v108, v109
	global_store_dwordx4 v[156:157], v[110:113], off offset:256 nt
	v_lshl_add_u64 v[156:157], v[156:157], 0, s[100:101]
	v_pk_mul_f32 v[234:235], v[26:27], v[242:243] op_sel_hi:[1,0]
	v_exp_f32_e32 v234, v234
	v_exp_f32_e32 v235, v235
	v_pk_mul_f32 v[236:237], v[28:29], v[242:243] op_sel_hi:[1,0]
	v_exp_f32_e32 v236, v236
	v_exp_f32_e32 v237, v237
	v_pk_mul_f32 v[238:239], v[34:35], v[242:243] op_sel_hi:[1,0]
	v_exp_f32_e32 v238, v238
	v_exp_f32_e32 v239, v239
	v_pk_mul_f32 v[240:241], v[36:37], v[242:243] op_sel_hi:[1,0]
	v_exp_f32_e32 v240, v240
	v_exp_f32_e32 v241, v241
	v_pk_add_f32 v[234:235], v[234:235], 1.0 op_sel_hi:[1,0]
	v_rcp_f32_e32 v234, v234
	v_rcp_f32_e32 v235, v235
	v_pk_add_f32 v[236:237], v[236:237], 1.0 op_sel_hi:[1,0]
	v_rcp_f32_e32 v236, v236
	v_rcp_f32_e32 v237, v237
	v_pk_add_f32 v[238:239], v[238:239], 1.0 op_sel_hi:[1,0]
	v_rcp_f32_e32 v238, v238
	v_rcp_f32_e32 v239, v239
	v_pk_add_f32 v[240:241], v[240:241], 1.0 op_sel_hi:[1,0]
	v_rcp_f32_e32 v240, v240
	v_rcp_f32_e32 v241, v241
	v_pk_mul_f32 v[26:27], v[26:27], v[234:235]
	v_pk_mul_f32 v[26:27], v[26:27], v[94:95]
	v_pk_mul_f32 v[28:29], v[28:29], v[236:237]
	v_pk_mul_f32 v[28:29], v[28:29], v[96:97]
	v_pk_mul_f32 v[34:35], v[34:35], v[238:239]
	v_pk_mul_f32 v[34:35], v[34:35], v[90:91]
	v_pk_mul_f32 v[36:37], v[36:37], v[240:241]
	v_pk_mul_f32 v[36:37], v[36:37], v[92:93]
	v_cvt_pk_bf16_f32 v34, v34, v35
	v_cvt_pk_bf16_f32 v35, v36, v37
	v_cvt_pk_bf16_f32 v36, v26, v27
	v_cvt_pk_bf16_f32 v37, v28, v29
	global_store_dwordx4 v[156:157], v[34:37], off nt
	v_pk_mul_f32 v[234:235], v[98:99], v[242:243] op_sel_hi:[1,0]
	v_exp_f32_e32 v234, v234
	v_exp_f32_e32 v235, v235
	v_pk_mul_f32 v[236:237], v[100:101], v[242:243] op_sel_hi:[1,0]
	v_exp_f32_e32 v236, v236
	v_exp_f32_e32 v237, v237
	v_pk_mul_f32 v[238:239], v[102:103], v[242:243] op_sel_hi:[1,0]
	v_exp_f32_e32 v238, v238
	v_exp_f32_e32 v239, v239
	v_pk_mul_f32 v[240:241], v[104:105], v[242:243] op_sel_hi:[1,0]
	v_exp_f32_e32 v240, v240
	v_exp_f32_e32 v241, v241
	v_pk_add_f32 v[234:235], v[234:235], 1.0 op_sel_hi:[1,0]
	v_rcp_f32_e32 v234, v234
	v_rcp_f32_e32 v235, v235
	v_pk_add_f32 v[236:237], v[236:237], 1.0 op_sel_hi:[1,0]
	v_rcp_f32_e32 v236, v236
	v_rcp_f32_e32 v237, v237
	v_pk_add_f32 v[238:239], v[238:239], 1.0 op_sel_hi:[1,0]
	v_rcp_f32_e32 v238, v238
	v_rcp_f32_e32 v239, v239
	v_pk_add_f32 v[240:241], v[240:241], 1.0 op_sel_hi:[1,0]
	v_rcp_f32_e32 v240, v240
	v_rcp_f32_e32 v241, v241
	v_pk_mul_f32 v[98:99], v[98:99], v[234:235]
	v_pk_mul_f32 v[98:99], v[98:99], v[94:95]
	v_pk_mul_f32 v[100:101], v[100:101], v[236:237]
	v_pk_mul_f32 v[100:101], v[100:101], v[96:97]
	v_pk_mul_f32 v[102:103], v[102:103], v[238:239]
	v_pk_mul_f32 v[102:103], v[102:103], v[90:91]
	v_pk_mul_f32 v[104:105], v[104:105], v[240:241]
	v_pk_mul_f32 v[104:105], v[104:105], v[92:93]
	v_cvt_pk_bf16_f32 v102, v102, v103
	v_cvt_pk_bf16_f32 v103, v104, v105
	v_cvt_pk_bf16_f32 v104, v98, v99
	v_cvt_pk_bf16_f32 v105, v100, v101
	global_store_dwordx4 v[156:157], v[102:105], off offset:256 nt
	v_lshl_add_u64 v[156:157], v[156:157], 0, s[98:99]
	v_pk_mul_f32 v[234:235], v[18:19], v[242:243] op_sel_hi:[1,0]
	v_exp_f32_e32 v234, v234
	v_exp_f32_e32 v235, v235
	v_pk_mul_f32 v[236:237], v[20:21], v[242:243] op_sel_hi:[1,0]
	v_exp_f32_e32 v236, v236
	v_exp_f32_e32 v237, v237
	v_pk_mul_f32 v[238:239], v[22:23], v[242:243] op_sel_hi:[1,0]
	v_exp_f32_e32 v238, v238
	v_exp_f32_e32 v239, v239
	v_pk_mul_f32 v[240:241], v[24:25], v[242:243] op_sel_hi:[1,0]
	v_exp_f32_e32 v240, v240
	v_exp_f32_e32 v241, v241
	v_pk_add_f32 v[234:235], v[234:235], 1.0 op_sel_hi:[1,0]
	v_rcp_f32_e32 v234, v234
	v_rcp_f32_e32 v235, v235
	v_pk_add_f32 v[236:237], v[236:237], 1.0 op_sel_hi:[1,0]
	v_rcp_f32_e32 v236, v236
	v_rcp_f32_e32 v237, v237
	v_pk_add_f32 v[238:239], v[238:239], 1.0 op_sel_hi:[1,0]
	v_rcp_f32_e32 v238, v238
	v_rcp_f32_e32 v239, v239
	v_pk_add_f32 v[240:241], v[240:241], 1.0 op_sel_hi:[1,0]
	v_rcp_f32_e32 v240, v240
	v_rcp_f32_e32 v241, v241
	v_pk_mul_f32 v[18:19], v[18:19], v[234:235]
	v_pk_mul_f32 v[18:19], v[18:19], v[94:95]
	v_pk_mul_f32 v[20:21], v[20:21], v[236:237]
	v_pk_mul_f32 v[20:21], v[20:21], v[96:97]
	v_pk_mul_f32 v[22:23], v[22:23], v[238:239]
	v_pk_mul_f32 v[22:23], v[22:23], v[90:91]
	v_pk_mul_f32 v[24:25], v[24:25], v[240:241]
	v_pk_mul_f32 v[24:25], v[24:25], v[92:93]
	v_cvt_pk_bf16_f32 v22, v22, v23
	v_cvt_pk_bf16_f32 v23, v24, v25
	v_cvt_pk_bf16_f32 v24, v18, v19
	v_cvt_pk_bf16_f32 v25, v20, v21
	global_store_dwordx4 v[156:157], v[22:25], off nt
	v_pk_mul_f32 v[234:235], v[82:83], v[242:243] op_sel_hi:[1,0]
	v_exp_f32_e32 v234, v234
	v_exp_f32_e32 v235, v235
	v_pk_mul_f32 v[236:237], v[84:85], v[242:243] op_sel_hi:[1,0]
	v_exp_f32_e32 v236, v236
	v_exp_f32_e32 v237, v237
	v_pk_mul_f32 v[238:239], v[86:87], v[242:243] op_sel_hi:[1,0]
	v_exp_f32_e32 v238, v238
	v_exp_f32_e32 v239, v239
	v_pk_mul_f32 v[240:241], v[88:89], v[242:243] op_sel_hi:[1,0]
	v_exp_f32_e32 v240, v240
	v_exp_f32_e32 v241, v241
	v_pk_add_f32 v[234:235], v[234:235], 1.0 op_sel_hi:[1,0]
	v_rcp_f32_e32 v234, v234
	v_rcp_f32_e32 v235, v235
	v_pk_add_f32 v[236:237], v[236:237], 1.0 op_sel_hi:[1,0]
	v_rcp_f32_e32 v236, v236
	v_rcp_f32_e32 v237, v237
	v_pk_add_f32 v[238:239], v[238:239], 1.0 op_sel_hi:[1,0]
	v_rcp_f32_e32 v238, v238
	v_rcp_f32_e32 v239, v239
	v_pk_add_f32 v[240:241], v[240:241], 1.0 op_sel_hi:[1,0]
	v_rcp_f32_e32 v240, v240
	v_rcp_f32_e32 v241, v241
	v_pk_mul_f32 v[82:83], v[82:83], v[234:235]
	v_pk_mul_f32 v[82:83], v[82:83], v[94:95]
	v_pk_mul_f32 v[84:85], v[84:85], v[236:237]
	v_pk_mul_f32 v[84:85], v[84:85], v[96:97]
	v_pk_mul_f32 v[86:87], v[86:87], v[238:239]
	v_pk_mul_f32 v[86:87], v[86:87], v[90:91]
	v_pk_mul_f32 v[88:89], v[88:89], v[240:241]
	v_pk_mul_f32 v[88:89], v[88:89], v[92:93]
	v_cvt_pk_bf16_f32 v86, v86, v87
	v_cvt_pk_bf16_f32 v87, v88, v89
	v_cvt_pk_bf16_f32 v88, v82, v83
	v_cvt_pk_bf16_f32 v89, v84, v85
	global_store_dwordx4 v[156:157], v[86:89], off offset:256 nt
	v_lshl_add_u64 v[156:157], v[156:157], 0, s[98:99]
	v_pk_mul_f32 v[234:235], v[10:11], v[242:243] op_sel_hi:[1,0]
	v_exp_f32_e32 v234, v234
	v_exp_f32_e32 v235, v235
	v_pk_mul_f32 v[236:237], v[12:13], v[242:243] op_sel_hi:[1,0]
	v_exp_f32_e32 v236, v236
	v_exp_f32_e32 v237, v237
	v_pk_mul_f32 v[238:239], v[14:15], v[242:243] op_sel_hi:[1,0]
	v_exp_f32_e32 v238, v238
	v_exp_f32_e32 v239, v239
	v_pk_mul_f32 v[240:241], v[16:17], v[242:243] op_sel_hi:[1,0]
	v_exp_f32_e32 v240, v240
	v_exp_f32_e32 v241, v241
	v_pk_add_f32 v[234:235], v[234:235], 1.0 op_sel_hi:[1,0]
	v_rcp_f32_e32 v234, v234
	v_rcp_f32_e32 v235, v235
	v_pk_add_f32 v[236:237], v[236:237], 1.0 op_sel_hi:[1,0]
	v_rcp_f32_e32 v236, v236
	v_rcp_f32_e32 v237, v237
	v_pk_add_f32 v[238:239], v[238:239], 1.0 op_sel_hi:[1,0]
	v_rcp_f32_e32 v238, v238
	v_rcp_f32_e32 v239, v239
	v_pk_add_f32 v[240:241], v[240:241], 1.0 op_sel_hi:[1,0]
	v_rcp_f32_e32 v240, v240
	v_rcp_f32_e32 v241, v241
	v_pk_mul_f32 v[10:11], v[10:11], v[234:235]
	v_pk_mul_f32 v[10:11], v[10:11], v[94:95]
	v_pk_mul_f32 v[12:13], v[12:13], v[236:237]
	v_pk_mul_f32 v[12:13], v[12:13], v[96:97]
	v_pk_mul_f32 v[14:15], v[14:15], v[238:239]
	v_pk_mul_f32 v[14:15], v[14:15], v[90:91]
	v_pk_mul_f32 v[16:17], v[16:17], v[240:241]
	v_pk_mul_f32 v[16:17], v[16:17], v[92:93]
	v_cvt_pk_bf16_f32 v14, v14, v15
	v_cvt_pk_bf16_f32 v15, v16, v17
	v_cvt_pk_bf16_f32 v16, v10, v11
	v_cvt_pk_bf16_f32 v17, v12, v13
	global_store_dwordx4 v[156:157], v[14:17], off nt
	v_pk_mul_f32 v[234:235], v[74:75], v[242:243] op_sel_hi:[1,0]
	v_exp_f32_e32 v234, v234
	v_exp_f32_e32 v235, v235
	v_pk_mul_f32 v[236:237], v[76:77], v[242:243] op_sel_hi:[1,0]
	v_exp_f32_e32 v236, v236
	v_exp_f32_e32 v237, v237
	v_pk_mul_f32 v[238:239], v[78:79], v[242:243] op_sel_hi:[1,0]
	v_exp_f32_e32 v238, v238
	v_exp_f32_e32 v239, v239
	v_pk_mul_f32 v[240:241], v[80:81], v[242:243] op_sel_hi:[1,0]
	v_exp_f32_e32 v240, v240
	v_exp_f32_e32 v241, v241
	v_pk_add_f32 v[234:235], v[234:235], 1.0 op_sel_hi:[1,0]
	v_rcp_f32_e32 v234, v234
	v_rcp_f32_e32 v235, v235
	v_pk_add_f32 v[236:237], v[236:237], 1.0 op_sel_hi:[1,0]
	v_rcp_f32_e32 v236, v236
	v_rcp_f32_e32 v237, v237
	v_pk_add_f32 v[238:239], v[238:239], 1.0 op_sel_hi:[1,0]
	v_rcp_f32_e32 v238, v238
	v_rcp_f32_e32 v239, v239
	v_pk_add_f32 v[240:241], v[240:241], 1.0 op_sel_hi:[1,0]
	v_rcp_f32_e32 v240, v240
	v_rcp_f32_e32 v241, v241
	v_pk_mul_f32 v[74:75], v[74:75], v[234:235]
	v_pk_mul_f32 v[74:75], v[74:75], v[94:95]
	v_pk_mul_f32 v[76:77], v[76:77], v[236:237]
	v_pk_mul_f32 v[76:77], v[76:77], v[96:97]
	v_pk_mul_f32 v[78:79], v[78:79], v[238:239]
	v_pk_mul_f32 v[78:79], v[78:79], v[90:91]
	v_pk_mul_f32 v[80:81], v[80:81], v[240:241]
	v_pk_mul_f32 v[80:81], v[80:81], v[92:93]
	v_cvt_pk_bf16_f32 v78, v78, v79
	v_cvt_pk_bf16_f32 v79, v80, v81
	v_cvt_pk_bf16_f32 v80, v74, v75
	v_cvt_pk_bf16_f32 v81, v76, v77
	global_store_dwordx4 v[156:157], v[78:81], off offset:256 nt
	v_lshl_add_u64 v[156:157], v[156:157], 0, s[98:99]
	v_pk_mul_f32 v[234:235], v[2:3], v[242:243] op_sel_hi:[1,0]
	v_exp_f32_e32 v234, v234
	v_exp_f32_e32 v235, v235
	v_pk_mul_f32 v[236:237], v[4:5], v[242:243] op_sel_hi:[1,0]
	v_exp_f32_e32 v236, v236
	v_exp_f32_e32 v237, v237
	v_pk_mul_f32 v[238:239], v[6:7], v[242:243] op_sel_hi:[1,0]
	v_exp_f32_e32 v238, v238
	v_exp_f32_e32 v239, v239
	v_pk_mul_f32 v[240:241], v[8:9], v[242:243] op_sel_hi:[1,0]
	v_exp_f32_e32 v240, v240
	v_exp_f32_e32 v241, v241
	v_pk_add_f32 v[234:235], v[234:235], 1.0 op_sel_hi:[1,0]
	v_rcp_f32_e32 v234, v234
	v_rcp_f32_e32 v235, v235
	v_pk_add_f32 v[236:237], v[236:237], 1.0 op_sel_hi:[1,0]
	v_rcp_f32_e32 v236, v236
	v_rcp_f32_e32 v237, v237
	v_pk_add_f32 v[238:239], v[238:239], 1.0 op_sel_hi:[1,0]
	v_rcp_f32_e32 v238, v238
	v_rcp_f32_e32 v239, v239
	v_pk_add_f32 v[240:241], v[240:241], 1.0 op_sel_hi:[1,0]
	v_rcp_f32_e32 v240, v240
	v_rcp_f32_e32 v241, v241
	v_pk_mul_f32 v[2:3], v[2:3], v[234:235]
	v_pk_mul_f32 v[2:3], v[2:3], v[94:95]
	v_pk_mul_f32 v[4:5], v[4:5], v[236:237]
	v_pk_mul_f32 v[4:5], v[4:5], v[96:97]
	v_pk_mul_f32 v[6:7], v[6:7], v[238:239]
	v_pk_mul_f32 v[6:7], v[6:7], v[90:91]
	v_pk_mul_f32 v[8:9], v[8:9], v[240:241]
	v_pk_mul_f32 v[8:9], v[8:9], v[92:93]
	v_cvt_pk_bf16_f32 v6, v6, v7
	v_cvt_pk_bf16_f32 v7, v8, v9
	v_cvt_pk_bf16_f32 v8, v2, v3
	v_cvt_pk_bf16_f32 v9, v4, v5
	global_store_dwordx4 v[156:157], v[6:9], off nt
	v_pk_mul_f32 v[234:235], v[30:31], v[242:243] op_sel_hi:[1,0]
	v_exp_f32_e32 v234, v234
	v_exp_f32_e32 v235, v235
	v_pk_mul_f32 v[236:237], v[32:33], v[242:243] op_sel_hi:[1,0]
	v_exp_f32_e32 v236, v236
	v_exp_f32_e32 v237, v237
	v_pk_mul_f32 v[238:239], v[38:39], v[242:243] op_sel_hi:[1,0]
	v_exp_f32_e32 v238, v238
	v_exp_f32_e32 v239, v239
	v_pk_mul_f32 v[240:241], v[40:41], v[242:243] op_sel_hi:[1,0]
	v_exp_f32_e32 v240, v240
	v_exp_f32_e32 v241, v241
	v_pk_add_f32 v[234:235], v[234:235], 1.0 op_sel_hi:[1,0]
	v_rcp_f32_e32 v234, v234
	v_rcp_f32_e32 v235, v235
	v_pk_add_f32 v[236:237], v[236:237], 1.0 op_sel_hi:[1,0]
	v_rcp_f32_e32 v236, v236
	v_rcp_f32_e32 v237, v237
	v_pk_add_f32 v[238:239], v[238:239], 1.0 op_sel_hi:[1,0]
	v_rcp_f32_e32 v238, v238
	v_rcp_f32_e32 v239, v239
	v_pk_add_f32 v[240:241], v[240:241], 1.0 op_sel_hi:[1,0]
	v_rcp_f32_e32 v240, v240
	v_rcp_f32_e32 v241, v241
	v_pk_mul_f32 v[30:31], v[30:31], v[234:235]
	v_pk_mul_f32 v[30:31], v[30:31], v[94:95]
	v_pk_mul_f32 v[32:33], v[32:33], v[236:237]
	v_pk_mul_f32 v[32:33], v[32:33], v[96:97]
	v_pk_mul_f32 v[38:39], v[38:39], v[238:239]
	v_pk_mul_f32 v[38:39], v[38:39], v[90:91]
	v_pk_mul_f32 v[40:41], v[40:41], v[240:241]
	v_pk_mul_f32 v[40:41], v[40:41], v[92:93]
	v_cvt_pk_bf16_f32 v38, v38, v39
	v_cvt_pk_bf16_f32 v39, v40, v41
	v_cvt_pk_bf16_f32 v40, v30, v31
	v_cvt_pk_bf16_f32 v41, v32, v33
	global_store_dwordx4 v[156:157], v[38:41], off offset:256 nt
	s_branch .Lepn0_dn
.Lepn0_m3:
	v_readlane_b32 s8, v249, 43
	v_readlane_b32 s9, v249, 44
	v_lshl_or_b32 v154, s78, 8, v163
	v_ashrrev_i32_e32 v155, 31, v154
	v_mov_b64_e32 v[156:157], s[8:9]
	v_mad_i64_i32 v[156:157], s[8:9], v152, s76, v[156:157]
	v_lshl_add_u64 v[156:157], v[154:155], 1, v[156:157]
	s_lshl_b32 s98, s76, 4
	s_mov_b32 s99, 0
	s_mul_i32 s100, s76, 0x50
	s_mov_b32 s101, 0
	v_mov_b32_e32 v242, 0xbfb8aa3b
	v_pk_mul_f32 v[234:235], v[66:67], v[242:243] op_sel_hi:[1,0]
	v_exp_f32_e32 v234, v234
	v_exp_f32_e32 v235, v235
	v_pk_mul_f32 v[236:237], v[68:69], v[242:243] op_sel_hi:[1,0]
	v_exp_f32_e32 v236, v236
	v_exp_f32_e32 v237, v237
	v_pk_mul_f32 v[238:239], v[70:71], v[242:243] op_sel_hi:[1,0]
	v_exp_f32_e32 v238, v238
	v_exp_f32_e32 v239, v239
	v_pk_mul_f32 v[240:241], v[72:73], v[242:243] op_sel_hi:[1,0]
	v_exp_f32_e32 v240, v240
	v_exp_f32_e32 v241, v241
	v_pk_add_f32 v[234:235], v[234:235], 1.0 op_sel_hi:[1,0]
	v_rcp_f32_e32 v234, v234
	v_rcp_f32_e32 v235, v235
	v_pk_add_f32 v[236:237], v[236:237], 1.0 op_sel_hi:[1,0]
	v_rcp_f32_e32 v236, v236
	v_rcp_f32_e32 v237, v237
	v_pk_add_f32 v[238:239], v[238:239], 1.0 op_sel_hi:[1,0]
	v_rcp_f32_e32 v238, v238
	v_rcp_f32_e32 v239, v239
	v_pk_add_f32 v[240:241], v[240:241], 1.0 op_sel_hi:[1,0]
	v_rcp_f32_e32 v240, v240
	v_rcp_f32_e32 v241, v241
	v_cvt_pk_bf16_f32 v70, v238, v239
	v_cvt_pk_bf16_f32 v71, v240, v241
	v_cvt_pk_bf16_f32 v72, v234, v235
	v_cvt_pk_bf16_f32 v73, v236, v237
	global_store_dwordx4 v[156:157], v[70:73], off nt
	v_pk_mul_f32 v[234:235], v[130:131], v[242:243] op_sel_hi:[1,0]
	v_exp_f32_e32 v234, v234
	v_exp_f32_e32 v235, v235
	v_pk_mul_f32 v[236:237], v[132:133], v[242:243] op_sel_hi:[1,0]
	v_exp_f32_e32 v236, v236
	v_exp_f32_e32 v237, v237
	v_pk_mul_f32 v[238:239], v[134:135], v[242:243] op_sel_hi:[1,0]
	v_exp_f32_e32 v238, v238
	v_exp_f32_e32 v239, v239
	v_pk_mul_f32 v[240:241], v[136:137], v[242:243] op_sel_hi:[1,0]
	v_exp_f32_e32 v240, v240
	v_exp_f32_e32 v241, v241
	v_pk_add_f32 v[234:235], v[234:235], 1.0 op_sel_hi:[1,0]
	v_rcp_f32_e32 v234, v234
	v_rcp_f32_e32 v235, v235
	v_pk_add_f32 v[236:237], v[236:237], 1.0 op_sel_hi:[1,0]
	v_rcp_f32_e32 v236, v236
	v_rcp_f32_e32 v237, v237
	v_pk_add_f32 v[238:239], v[238:239], 1.0 op_sel_hi:[1,0]
	v_rcp_f32_e32 v238, v238
	v_rcp_f32_e32 v239, v239
	v_pk_add_f32 v[240:241], v[240:241], 1.0 op_sel_hi:[1,0]
	v_rcp_f32_e32 v240, v240
	v_rcp_f32_e32 v241, v241
	v_cvt_pk_bf16_f32 v134, v238, v239
	v_cvt_pk_bf16_f32 v135, v240, v241
	v_cvt_pk_bf16_f32 v136, v234, v235
	v_cvt_pk_bf16_f32 v137, v236, v237
	global_store_dwordx4 v[156:157], v[134:137], off offset:256 nt
	v_lshl_add_u64 v[156:157], v[156:157], 0, s[98:99]
	v_pk_mul_f32 v[234:235], v[58:59], v[242:243] op_sel_hi:[1,0]
	v_exp_f32_e32 v234, v234
	v_exp_f32_e32 v235, v235
	v_pk_mul_f32 v[236:237], v[60:61], v[242:243] op_sel_hi:[1,0]
	v_exp_f32_e32 v236, v236
	v_exp_f32_e32 v237, v237
	v_pk_mul_f32 v[238:239], v[62:63], v[242:243] op_sel_hi:[1,0]
	v_exp_f32_e32 v238, v238
	v_exp_f32_e32 v239, v239
	v_pk_mul_f32 v[240:241], v[64:65], v[242:243] op_sel_hi:[1,0]
	v_exp_f32_e32 v240, v240
	v_exp_f32_e32 v241, v241
	v_pk_add_f32 v[234:235], v[234:235], 1.0 op_sel_hi:[1,0]
	v_rcp_f32_e32 v234, v234
	v_rcp_f32_e32 v235, v235
	v_pk_add_f32 v[236:237], v[236:237], 1.0 op_sel_hi:[1,0]
	v_rcp_f32_e32 v236, v236
	v_rcp_f32_e32 v237, v237
	v_pk_add_f32 v[238:239], v[238:239], 1.0 op_sel_hi:[1,0]
	v_rcp_f32_e32 v238, v238
	v_rcp_f32_e32 v239, v239
	v_pk_add_f32 v[240:241], v[240:241], 1.0 op_sel_hi:[1,0]
	v_rcp_f32_e32 v240, v240
	v_rcp_f32_e32 v241, v241
	v_cvt_pk_bf16_f32 v62, v238, v239
	v_cvt_pk_bf16_f32 v63, v240, v241
	v_cvt_pk_bf16_f32 v64, v234, v235
	v_cvt_pk_bf16_f32 v65, v236, v237
	global_store_dwordx4 v[156:157], v[62:65], off nt
	v_pk_mul_f32 v[234:235], v[122:123], v[242:243] op_sel_hi:[1,0]
	v_exp_f32_e32 v234, v234
	v_exp_f32_e32 v235, v235
	v_pk_mul_f32 v[236:237], v[124:125], v[242:243] op_sel_hi:[1,0]
	v_exp_f32_e32 v236, v236
	v_exp_f32_e32 v237, v237
	v_pk_mul_f32 v[238:239], v[126:127], v[242:243] op_sel_hi:[1,0]
	v_exp_f32_e32 v238, v238
	v_exp_f32_e32 v239, v239
	v_pk_mul_f32 v[240:241], v[128:129], v[242:243] op_sel_hi:[1,0]
	v_exp_f32_e32 v240, v240
	v_exp_f32_e32 v241, v241
	v_pk_add_f32 v[234:235], v[234:235], 1.0 op_sel_hi:[1,0]
	v_rcp_f32_e32 v234, v234
	v_rcp_f32_e32 v235, v235
	v_pk_add_f32 v[236:237], v[236:237], 1.0 op_sel_hi:[1,0]
	v_rcp_f32_e32 v236, v236
	v_rcp_f32_e32 v237, v237
	v_pk_add_f32 v[238:239], v[238:239], 1.0 op_sel_hi:[1,0]
	v_rcp_f32_e32 v238, v238
	v_rcp_f32_e32 v239, v239
	v_pk_add_f32 v[240:241], v[240:241], 1.0 op_sel_hi:[1,0]
	v_rcp_f32_e32 v240, v240
	v_rcp_f32_e32 v241, v241
	v_cvt_pk_bf16_f32 v126, v238, v239
	v_cvt_pk_bf16_f32 v127, v240, v241
	v_cvt_pk_bf16_f32 v128, v234, v235
	v_cvt_pk_bf16_f32 v129, v236, v237
	global_store_dwordx4 v[156:157], v[126:129], off offset:256 nt
	v_lshl_add_u64 v[156:157], v[156:157], 0, s[98:99]
	v_pk_mul_f32 v[234:235], v[50:51], v[242:243] op_sel_hi:[1,0]
	v_exp_f32_e32 v234, v234
	v_exp_f32_e32 v235, v235
	v_pk_mul_f32 v[236:237], v[52:53], v[242:243] op_sel_hi:[1,0]
	v_exp_f32_e32 v236, v236
	v_exp_f32_e32 v237, v237
	v_pk_mul_f32 v[238:239], v[54:55], v[242:243] op_sel_hi:[1,0]
	v_exp_f32_e32 v238, v238
	v_exp_f32_e32 v239, v239
	v_pk_mul_f32 v[240:241], v[56:57], v[242:243] op_sel_hi:[1,0]
	v_exp_f32_e32 v240, v240
	v_exp_f32_e32 v241, v241
	v_pk_add_f32 v[234:235], v[234:235], 1.0 op_sel_hi:[1,0]
	v_rcp_f32_e32 v234, v234
	v_rcp_f32_e32 v235, v235
	v_pk_add_f32 v[236:237], v[236:237], 1.0 op_sel_hi:[1,0]
	v_rcp_f32_e32 v236, v236
	v_rcp_f32_e32 v237, v237
	v_pk_add_f32 v[238:239], v[238:239], 1.0 op_sel_hi:[1,0]
	v_rcp_f32_e32 v238, v238
	v_rcp_f32_e32 v239, v239
	v_pk_add_f32 v[240:241], v[240:241], 1.0 op_sel_hi:[1,0]
	v_rcp_f32_e32 v240, v240
	v_rcp_f32_e32 v241, v241
	v_cvt_pk_bf16_f32 v54, v238, v239
	v_cvt_pk_bf16_f32 v55, v240, v241
	v_cvt_pk_bf16_f32 v56, v234, v235
	v_cvt_pk_bf16_f32 v57, v236, v237
	global_store_dwordx4 v[156:157], v[54:57], off nt
	v_pk_mul_f32 v[234:235], v[114:115], v[242:243] op_sel_hi:[1,0]
	v_exp_f32_e32 v234, v234
	v_exp_f32_e32 v235, v235
	v_pk_mul_f32 v[236:237], v[116:117], v[242:243] op_sel_hi:[1,0]
	v_exp_f32_e32 v236, v236
	v_exp_f32_e32 v237, v237
	v_pk_mul_f32 v[238:239], v[118:119], v[242:243] op_sel_hi:[1,0]
	v_exp_f32_e32 v238, v238
	v_exp_f32_e32 v239, v239
	v_pk_mul_f32 v[240:241], v[120:121], v[242:243] op_sel_hi:[1,0]
	v_exp_f32_e32 v240, v240
	v_exp_f32_e32 v241, v241
	v_pk_add_f32 v[234:235], v[234:235], 1.0 op_sel_hi:[1,0]
	v_rcp_f32_e32 v234, v234
	v_rcp_f32_e32 v235, v235
	v_pk_add_f32 v[236:237], v[236:237], 1.0 op_sel_hi:[1,0]
	v_rcp_f32_e32 v236, v236
	v_rcp_f32_e32 v237, v237
	v_pk_add_f32 v[238:239], v[238:239], 1.0 op_sel_hi:[1,0]
	v_rcp_f32_e32 v238, v238
	v_rcp_f32_e32 v239, v239
	v_pk_add_f32 v[240:241], v[240:241], 1.0 op_sel_hi:[1,0]
	v_rcp_f32_e32 v240, v240
	v_rcp_f32_e32 v241, v241
	v_cvt_pk_bf16_f32 v118, v238, v239
	v_cvt_pk_bf16_f32 v119, v240, v241
	v_cvt_pk_bf16_f32 v120, v234, v235
	v_cvt_pk_bf16_f32 v121, v236, v237
	global_store_dwordx4 v[156:157], v[118:121], off offset:256 nt
	v_lshl_add_u64 v[156:157], v[156:157], 0, s[98:99]
	v_pk_mul_f32 v[234:235], v[42:43], v[242:243] op_sel_hi:[1,0]
	v_exp_f32_e32 v234, v234
	v_exp_f32_e32 v235, v235
	v_pk_mul_f32 v[236:237], v[44:45], v[242:243] op_sel_hi:[1,0]
	v_exp_f32_e32 v236, v236
	v_exp_f32_e32 v237, v237
	v_pk_mul_f32 v[238:239], v[46:47], v[242:243] op_sel_hi:[1,0]
	v_exp_f32_e32 v238, v238
	v_exp_f32_e32 v239, v239
	v_pk_mul_f32 v[240:241], v[48:49], v[242:243] op_sel_hi:[1,0]
	v_exp_f32_e32 v240, v240
	v_exp_f32_e32 v241, v241
	v_pk_add_f32 v[234:235], v[234:235], 1.0 op_sel_hi:[1,0]
	v_rcp_f32_e32 v234, v234
	v_rcp_f32_e32 v235, v235
	v_pk_add_f32 v[236:237], v[236:237], 1.0 op_sel_hi:[1,0]
	v_rcp_f32_e32 v236, v236
	v_rcp_f32_e32 v237, v237
	v_pk_add_f32 v[238:239], v[238:239], 1.0 op_sel_hi:[1,0]
	v_rcp_f32_e32 v238, v238
	v_rcp_f32_e32 v239, v239
	v_pk_add_f32 v[240:241], v[240:241], 1.0 op_sel_hi:[1,0]
	v_rcp_f32_e32 v240, v240
	v_rcp_f32_e32 v241, v241
	v_cvt_pk_bf16_f32 v46, v238, v239
	v_cvt_pk_bf16_f32 v47, v240, v241
	v_cvt_pk_bf16_f32 v48, v234, v235
	v_cvt_pk_bf16_f32 v49, v236, v237
	global_store_dwordx4 v[156:157], v[46:49], off nt
	v_pk_mul_f32 v[234:235], v[106:107], v[242:243] op_sel_hi:[1,0]
	v_exp_f32_e32 v234, v234
	v_exp_f32_e32 v235, v235
	v_pk_mul_f32 v[236:237], v[108:109], v[242:243] op_sel_hi:[1,0]
	v_exp_f32_e32 v236, v236
	v_exp_f32_e32 v237, v237
	v_pk_mul_f32 v[238:239], v[110:111], v[242:243] op_sel_hi:[1,0]
	v_exp_f32_e32 v238, v238
	v_exp_f32_e32 v239, v239
	v_pk_mul_f32 v[240:241], v[112:113], v[242:243] op_sel_hi:[1,0]
	v_exp_f32_e32 v240, v240
	v_exp_f32_e32 v241, v241
	v_pk_add_f32 v[234:235], v[234:235], 1.0 op_sel_hi:[1,0]
	v_rcp_f32_e32 v234, v234
	v_rcp_f32_e32 v235, v235
	v_pk_add_f32 v[236:237], v[236:237], 1.0 op_sel_hi:[1,0]
	v_rcp_f32_e32 v236, v236
	v_rcp_f32_e32 v237, v237
	v_pk_add_f32 v[238:239], v[238:239], 1.0 op_sel_hi:[1,0]
	v_rcp_f32_e32 v238, v238
	v_rcp_f32_e32 v239, v239
	v_pk_add_f32 v[240:241], v[240:241], 1.0 op_sel_hi:[1,0]
	v_rcp_f32_e32 v240, v240
	v_rcp_f32_e32 v241, v241
	v_cvt_pk_bf16_f32 v110, v238, v239
	v_cvt_pk_bf16_f32 v111, v240, v241
	v_cvt_pk_bf16_f32 v112, v234, v235
	v_cvt_pk_bf16_f32 v113, v236, v237
	global_store_dwordx4 v[156:157], v[110:113], off offset:256 nt
	v_lshl_add_u64 v[156:157], v[156:157], 0, s[100:101]
	v_pk_mul_f32 v[234:235], v[26:27], v[242:243] op_sel_hi:[1,0]
	v_exp_f32_e32 v234, v234
	v_exp_f32_e32 v235, v235
	v_pk_mul_f32 v[236:237], v[28:29], v[242:243] op_sel_hi:[1,0]
	v_exp_f32_e32 v236, v236
	v_exp_f32_e32 v237, v237
	v_pk_mul_f32 v[238:239], v[34:35], v[242:243] op_sel_hi:[1,0]
	v_exp_f32_e32 v238, v238
	v_exp_f32_e32 v239, v239
	v_pk_mul_f32 v[240:241], v[36:37], v[242:243] op_sel_hi:[1,0]
	v_exp_f32_e32 v240, v240
	v_exp_f32_e32 v241, v241
	v_pk_add_f32 v[234:235], v[234:235], 1.0 op_sel_hi:[1,0]
	v_rcp_f32_e32 v234, v234
	v_rcp_f32_e32 v235, v235
	v_pk_add_f32 v[236:237], v[236:237], 1.0 op_sel_hi:[1,0]
	v_rcp_f32_e32 v236, v236
	v_rcp_f32_e32 v237, v237
	v_pk_add_f32 v[238:239], v[238:239], 1.0 op_sel_hi:[1,0]
	v_rcp_f32_e32 v238, v238
	v_rcp_f32_e32 v239, v239
	v_pk_add_f32 v[240:241], v[240:241], 1.0 op_sel_hi:[1,0]
	v_rcp_f32_e32 v240, v240
	v_rcp_f32_e32 v241, v241
	v_cvt_pk_bf16_f32 v34, v238, v239
	v_cvt_pk_bf16_f32 v35, v240, v241
	v_cvt_pk_bf16_f32 v36, v234, v235
	v_cvt_pk_bf16_f32 v37, v236, v237
	global_store_dwordx4 v[156:157], v[34:37], off nt
	v_pk_mul_f32 v[234:235], v[98:99], v[242:243] op_sel_hi:[1,0]
	v_exp_f32_e32 v234, v234
	v_exp_f32_e32 v235, v235
	v_pk_mul_f32 v[236:237], v[100:101], v[242:243] op_sel_hi:[1,0]
	v_exp_f32_e32 v236, v236
	v_exp_f32_e32 v237, v237
	v_pk_mul_f32 v[238:239], v[102:103], v[242:243] op_sel_hi:[1,0]
	v_exp_f32_e32 v238, v238
	v_exp_f32_e32 v239, v239
	v_pk_mul_f32 v[240:241], v[104:105], v[242:243] op_sel_hi:[1,0]
	v_exp_f32_e32 v240, v240
	v_exp_f32_e32 v241, v241
	v_pk_add_f32 v[234:235], v[234:235], 1.0 op_sel_hi:[1,0]
	v_rcp_f32_e32 v234, v234
	v_rcp_f32_e32 v235, v235
	v_pk_add_f32 v[236:237], v[236:237], 1.0 op_sel_hi:[1,0]
	v_rcp_f32_e32 v236, v236
	v_rcp_f32_e32 v237, v237
	v_pk_add_f32 v[238:239], v[238:239], 1.0 op_sel_hi:[1,0]
	v_rcp_f32_e32 v238, v238
	v_rcp_f32_e32 v239, v239
	v_pk_add_f32 v[240:241], v[240:241], 1.0 op_sel_hi:[1,0]
	v_rcp_f32_e32 v240, v240
	v_rcp_f32_e32 v241, v241
	v_cvt_pk_bf16_f32 v102, v238, v239
	v_cvt_pk_bf16_f32 v103, v240, v241
	v_cvt_pk_bf16_f32 v104, v234, v235
	v_cvt_pk_bf16_f32 v105, v236, v237
	global_store_dwordx4 v[156:157], v[102:105], off offset:256 nt
	v_lshl_add_u64 v[156:157], v[156:157], 0, s[98:99]
	v_pk_mul_f32 v[234:235], v[18:19], v[242:243] op_sel_hi:[1,0]
	v_exp_f32_e32 v234, v234
	v_exp_f32_e32 v235, v235
	v_pk_mul_f32 v[236:237], v[20:21], v[242:243] op_sel_hi:[1,0]
	v_exp_f32_e32 v236, v236
	v_exp_f32_e32 v237, v237
	v_pk_mul_f32 v[238:239], v[22:23], v[242:243] op_sel_hi:[1,0]
	v_exp_f32_e32 v238, v238
	v_exp_f32_e32 v239, v239
	v_pk_mul_f32 v[240:241], v[24:25], v[242:243] op_sel_hi:[1,0]
	v_exp_f32_e32 v240, v240
	v_exp_f32_e32 v241, v241
	v_pk_add_f32 v[234:235], v[234:235], 1.0 op_sel_hi:[1,0]
	v_rcp_f32_e32 v234, v234
	v_rcp_f32_e32 v235, v235
	v_pk_add_f32 v[236:237], v[236:237], 1.0 op_sel_hi:[1,0]
	v_rcp_f32_e32 v236, v236
	v_rcp_f32_e32 v237, v237
	v_pk_add_f32 v[238:239], v[238:239], 1.0 op_sel_hi:[1,0]
	v_rcp_f32_e32 v238, v238
	v_rcp_f32_e32 v239, v239
	v_pk_add_f32 v[240:241], v[240:241], 1.0 op_sel_hi:[1,0]
	v_rcp_f32_e32 v240, v240
	v_rcp_f32_e32 v241, v241
	v_cvt_pk_bf16_f32 v22, v238, v239
	v_cvt_pk_bf16_f32 v23, v240, v241
	v_cvt_pk_bf16_f32 v24, v234, v235
	v_cvt_pk_bf16_f32 v25, v236, v237
	global_store_dwordx4 v[156:157], v[22:25], off nt
	v_pk_mul_f32 v[234:235], v[82:83], v[242:243] op_sel_hi:[1,0]
	v_exp_f32_e32 v234, v234
	v_exp_f32_e32 v235, v235
	v_pk_mul_f32 v[236:237], v[84:85], v[242:243] op_sel_hi:[1,0]
	v_exp_f32_e32 v236, v236
	v_exp_f32_e32 v237, v237
	v_pk_mul_f32 v[238:239], v[86:87], v[242:243] op_sel_hi:[1,0]
	v_exp_f32_e32 v238, v238
	v_exp_f32_e32 v239, v239
	v_pk_mul_f32 v[240:241], v[88:89], v[242:243] op_sel_hi:[1,0]
	v_exp_f32_e32 v240, v240
	v_exp_f32_e32 v241, v241
	v_pk_add_f32 v[234:235], v[234:235], 1.0 op_sel_hi:[1,0]
	v_rcp_f32_e32 v234, v234
	v_rcp_f32_e32 v235, v235
	v_pk_add_f32 v[236:237], v[236:237], 1.0 op_sel_hi:[1,0]
	v_rcp_f32_e32 v236, v236
	v_rcp_f32_e32 v237, v237
	v_pk_add_f32 v[238:239], v[238:239], 1.0 op_sel_hi:[1,0]
	v_rcp_f32_e32 v238, v238
	v_rcp_f32_e32 v239, v239
	v_pk_add_f32 v[240:241], v[240:241], 1.0 op_sel_hi:[1,0]
	v_rcp_f32_e32 v240, v240
	v_rcp_f32_e32 v241, v241
	v_cvt_pk_bf16_f32 v86, v238, v239
	v_cvt_pk_bf16_f32 v87, v240, v241
	v_cvt_pk_bf16_f32 v88, v234, v235
	v_cvt_pk_bf16_f32 v89, v236, v237
	global_store_dwordx4 v[156:157], v[86:89], off offset:256 nt
	v_lshl_add_u64 v[156:157], v[156:157], 0, s[98:99]
	v_pk_mul_f32 v[234:235], v[10:11], v[242:243] op_sel_hi:[1,0]
	v_exp_f32_e32 v234, v234
	v_exp_f32_e32 v235, v235
	v_pk_mul_f32 v[236:237], v[12:13], v[242:243] op_sel_hi:[1,0]
	v_exp_f32_e32 v236, v236
	v_exp_f32_e32 v237, v237
	v_pk_mul_f32 v[238:239], v[14:15], v[242:243] op_sel_hi:[1,0]
	v_exp_f32_e32 v238, v238
	v_exp_f32_e32 v239, v239
	v_pk_mul_f32 v[240:241], v[16:17], v[242:243] op_sel_hi:[1,0]
	v_exp_f32_e32 v240, v240
	v_exp_f32_e32 v241, v241
	v_pk_add_f32 v[234:235], v[234:235], 1.0 op_sel_hi:[1,0]
	v_rcp_f32_e32 v234, v234
	v_rcp_f32_e32 v235, v235
	v_pk_add_f32 v[236:237], v[236:237], 1.0 op_sel_hi:[1,0]
	v_rcp_f32_e32 v236, v236
	v_rcp_f32_e32 v237, v237
	v_pk_add_f32 v[238:239], v[238:239], 1.0 op_sel_hi:[1,0]
	v_rcp_f32_e32 v238, v238
	v_rcp_f32_e32 v239, v239
	v_pk_add_f32 v[240:241], v[240:241], 1.0 op_sel_hi:[1,0]
	v_rcp_f32_e32 v240, v240
	v_rcp_f32_e32 v241, v241
	v_cvt_pk_bf16_f32 v14, v238, v239
	v_cvt_pk_bf16_f32 v15, v240, v241
	v_cvt_pk_bf16_f32 v16, v234, v235
	v_cvt_pk_bf16_f32 v17, v236, v237
	global_store_dwordx4 v[156:157], v[14:17], off nt
	v_pk_mul_f32 v[234:235], v[74:75], v[242:243] op_sel_hi:[1,0]
	v_exp_f32_e32 v234, v234
	v_exp_f32_e32 v235, v235
	v_pk_mul_f32 v[236:237], v[76:77], v[242:243] op_sel_hi:[1,0]
	v_exp_f32_e32 v236, v236
	v_exp_f32_e32 v237, v237
	v_pk_mul_f32 v[238:239], v[78:79], v[242:243] op_sel_hi:[1,0]
	v_exp_f32_e32 v238, v238
	v_exp_f32_e32 v239, v239
	v_pk_mul_f32 v[240:241], v[80:81], v[242:243] op_sel_hi:[1,0]
	v_exp_f32_e32 v240, v240
	v_exp_f32_e32 v241, v241
	v_pk_add_f32 v[234:235], v[234:235], 1.0 op_sel_hi:[1,0]
	v_rcp_f32_e32 v234, v234
	v_rcp_f32_e32 v235, v235
	v_pk_add_f32 v[236:237], v[236:237], 1.0 op_sel_hi:[1,0]
	v_rcp_f32_e32 v236, v236
	v_rcp_f32_e32 v237, v237
	v_pk_add_f32 v[238:239], v[238:239], 1.0 op_sel_hi:[1,0]
	v_rcp_f32_e32 v238, v238
	v_rcp_f32_e32 v239, v239
	v_pk_add_f32 v[240:241], v[240:241], 1.0 op_sel_hi:[1,0]
	v_rcp_f32_e32 v240, v240
	v_rcp_f32_e32 v241, v241
	v_cvt_pk_bf16_f32 v78, v238, v239
	v_cvt_pk_bf16_f32 v79, v240, v241
	v_cvt_pk_bf16_f32 v80, v234, v235
	v_cvt_pk_bf16_f32 v81, v236, v237
	global_store_dwordx4 v[156:157], v[78:81], off offset:256 nt
	v_lshl_add_u64 v[156:157], v[156:157], 0, s[98:99]
	v_pk_mul_f32 v[234:235], v[2:3], v[242:243] op_sel_hi:[1,0]
	v_exp_f32_e32 v234, v234
	v_exp_f32_e32 v235, v235
	v_pk_mul_f32 v[236:237], v[4:5], v[242:243] op_sel_hi:[1,0]
	v_exp_f32_e32 v236, v236
	v_exp_f32_e32 v237, v237
	v_pk_mul_f32 v[238:239], v[6:7], v[242:243] op_sel_hi:[1,0]
	v_exp_f32_e32 v238, v238
	v_exp_f32_e32 v239, v239
	v_pk_mul_f32 v[240:241], v[8:9], v[242:243] op_sel_hi:[1,0]
	v_exp_f32_e32 v240, v240
	v_exp_f32_e32 v241, v241
	v_pk_add_f32 v[234:235], v[234:235], 1.0 op_sel_hi:[1,0]
	v_rcp_f32_e32 v234, v234
	v_rcp_f32_e32 v235, v235
	v_pk_add_f32 v[236:237], v[236:237], 1.0 op_sel_hi:[1,0]
	v_rcp_f32_e32 v236, v236
	v_rcp_f32_e32 v237, v237
	v_pk_add_f32 v[238:239], v[238:239], 1.0 op_sel_hi:[1,0]
	v_rcp_f32_e32 v238, v238
	v_rcp_f32_e32 v239, v239
	v_pk_add_f32 v[240:241], v[240:241], 1.0 op_sel_hi:[1,0]
	v_rcp_f32_e32 v240, v240
	v_rcp_f32_e32 v241, v241
	v_cvt_pk_bf16_f32 v6, v238, v239
	v_cvt_pk_bf16_f32 v7, v240, v241
	v_cvt_pk_bf16_f32 v8, v234, v235
	v_cvt_pk_bf16_f32 v9, v236, v237
	global_store_dwordx4 v[156:157], v[6:9], off nt
	v_pk_mul_f32 v[234:235], v[30:31], v[242:243] op_sel_hi:[1,0]
	v_exp_f32_e32 v234, v234
	v_exp_f32_e32 v235, v235
	v_pk_mul_f32 v[236:237], v[32:33], v[242:243] op_sel_hi:[1,0]
	v_exp_f32_e32 v236, v236
	v_exp_f32_e32 v237, v237
	v_pk_mul_f32 v[238:239], v[38:39], v[242:243] op_sel_hi:[1,0]
	v_exp_f32_e32 v238, v238
	v_exp_f32_e32 v239, v239
	v_pk_mul_f32 v[240:241], v[40:41], v[242:243] op_sel_hi:[1,0]
	v_exp_f32_e32 v240, v240
	v_exp_f32_e32 v241, v241
	v_pk_add_f32 v[234:235], v[234:235], 1.0 op_sel_hi:[1,0]
	v_rcp_f32_e32 v234, v234
	v_rcp_f32_e32 v235, v235
	v_pk_add_f32 v[236:237], v[236:237], 1.0 op_sel_hi:[1,0]
	v_rcp_f32_e32 v236, v236
	v_rcp_f32_e32 v237, v237
	v_pk_add_f32 v[238:239], v[238:239], 1.0 op_sel_hi:[1,0]
	v_rcp_f32_e32 v238, v238
	v_rcp_f32_e32 v239, v239
	v_pk_add_f32 v[240:241], v[240:241], 1.0 op_sel_hi:[1,0]
	v_rcp_f32_e32 v240, v240
	v_rcp_f32_e32 v241, v241
	v_cvt_pk_bf16_f32 v38, v238, v239
	v_cvt_pk_bf16_f32 v39, v240, v241
	v_cvt_pk_bf16_f32 v40, v234, v235
	v_cvt_pk_bf16_f32 v41, v236, v237
	global_store_dwordx4 v[156:157], v[38:41], off offset:256 nt
	s_branch .Lepn0_dn
.Lepn0_m0:
	v_readlane_b32 s8, v249, 43
	v_readlane_b32 s9, v249, 44
	v_lshl_or_b32 v154, s78, 8, v163
	v_ashrrev_i32_e32 v155, 31, v154
	v_mov_b64_e32 v[156:157], s[8:9]
	v_mad_i64_i32 v[156:157], s[8:9], v152, s76, v[156:157]
	v_lshl_add_u64 v[156:157], v[154:155], 1, v[156:157]
	s_lshl_b32 s98, s76, 4
	s_mov_b32 s99, 0
	s_mul_i32 s100, s76, 0x50
	s_mov_b32 s101, 0
	v_cvt_pk_bf16_f32 v70, v70, v71
	v_cvt_pk_bf16_f32 v71, v72, v73
	v_cvt_pk_bf16_f32 v72, v66, v67
	v_cvt_pk_bf16_f32 v73, v68, v69
	global_store_dwordx4 v[156:157], v[70:73], off nt
	v_cvt_pk_bf16_f32 v134, v134, v135
	v_cvt_pk_bf16_f32 v135, v136, v137
	v_cvt_pk_bf16_f32 v136, v130, v131
	v_cvt_pk_bf16_f32 v137, v132, v133
	global_store_dwordx4 v[156:157], v[134:137], off offset:256 nt
	v_lshl_add_u64 v[156:157], v[156:157], 0, s[98:99]
	v_cvt_pk_bf16_f32 v62, v62, v63
	v_cvt_pk_bf16_f32 v63, v64, v65
	v_cvt_pk_bf16_f32 v64, v58, v59
	v_cvt_pk_bf16_f32 v65, v60, v61
	global_store_dwordx4 v[156:157], v[62:65], off nt
	v_cvt_pk_bf16_f32 v126, v126, v127
	v_cvt_pk_bf16_f32 v127, v128, v129
	v_cvt_pk_bf16_f32 v128, v122, v123
	v_cvt_pk_bf16_f32 v129, v124, v125
	global_store_dwordx4 v[156:157], v[126:129], off offset:256 nt
	v_lshl_add_u64 v[156:157], v[156:157], 0, s[98:99]
	v_cvt_pk_bf16_f32 v54, v54, v55
	v_cvt_pk_bf16_f32 v55, v56, v57
	v_cvt_pk_bf16_f32 v56, v50, v51
	v_cvt_pk_bf16_f32 v57, v52, v53
	global_store_dwordx4 v[156:157], v[54:57], off nt
	v_cvt_pk_bf16_f32 v118, v118, v119
	v_cvt_pk_bf16_f32 v119, v120, v121
	v_cvt_pk_bf16_f32 v120, v114, v115
	v_cvt_pk_bf16_f32 v121, v116, v117
	global_store_dwordx4 v[156:157], v[118:121], off offset:256 nt
	v_lshl_add_u64 v[156:157], v[156:157], 0, s[98:99]
	v_cvt_pk_bf16_f32 v46, v46, v47
	v_cvt_pk_bf16_f32 v47, v48, v49
	v_cvt_pk_bf16_f32 v48, v42, v43
	v_cvt_pk_bf16_f32 v49, v44, v45
	global_store_dwordx4 v[156:157], v[46:49], off nt
	v_cvt_pk_bf16_f32 v110, v110, v111
	v_cvt_pk_bf16_f32 v111, v112, v113
	v_cvt_pk_bf16_f32 v112, v106, v107
	v_cvt_pk_bf16_f32 v113, v108, v109
	global_store_dwordx4 v[156:157], v[110:113], off offset:256 nt
	v_lshl_add_u64 v[156:157], v[156:157], 0, s[100:101]
	v_cvt_pk_bf16_f32 v34, v34, v35
	v_cvt_pk_bf16_f32 v35, v36, v37
	v_cvt_pk_bf16_f32 v36, v26, v27
	v_cvt_pk_bf16_f32 v37, v28, v29
	global_store_dwordx4 v[156:157], v[34:37], off nt
	v_cvt_pk_bf16_f32 v102, v102, v103
	v_cvt_pk_bf16_f32 v103, v104, v105
	v_cvt_pk_bf16_f32 v104, v98, v99
	v_cvt_pk_bf16_f32 v105, v100, v101
	global_store_dwordx4 v[156:157], v[102:105], off offset:256 nt
	v_lshl_add_u64 v[156:157], v[156:157], 0, s[98:99]
	v_cvt_pk_bf16_f32 v22, v22, v23
	v_cvt_pk_bf16_f32 v23, v24, v25
	v_cvt_pk_bf16_f32 v24, v18, v19
	v_cvt_pk_bf16_f32 v25, v20, v21
	global_store_dwordx4 v[156:157], v[22:25], off nt
	v_cvt_pk_bf16_f32 v86, v86, v87
	v_cvt_pk_bf16_f32 v87, v88, v89
	v_cvt_pk_bf16_f32 v88, v82, v83
	v_cvt_pk_bf16_f32 v89, v84, v85
	global_store_dwordx4 v[156:157], v[86:89], off offset:256 nt
	v_lshl_add_u64 v[156:157], v[156:157], 0, s[98:99]
	v_cvt_pk_bf16_f32 v14, v14, v15
	v_cvt_pk_bf16_f32 v15, v16, v17
	v_cvt_pk_bf16_f32 v16, v10, v11
	v_cvt_pk_bf16_f32 v17, v12, v13
	global_store_dwordx4 v[156:157], v[14:17], off nt
	v_cvt_pk_bf16_f32 v78, v78, v79
	v_cvt_pk_bf16_f32 v79, v80, v81
	v_cvt_pk_bf16_f32 v80, v74, v75
	v_cvt_pk_bf16_f32 v81, v76, v77
	global_store_dwordx4 v[156:157], v[78:81], off offset:256 nt
	v_lshl_add_u64 v[156:157], v[156:157], 0, s[98:99]
	v_cvt_pk_bf16_f32 v6, v6, v7
	v_cvt_pk_bf16_f32 v7, v8, v9
	v_cvt_pk_bf16_f32 v8, v2, v3
	v_cvt_pk_bf16_f32 v9, v4, v5
	global_store_dwordx4 v[156:157], v[6:9], off nt
	v_cvt_pk_bf16_f32 v38, v38, v39
	v_cvt_pk_bf16_f32 v39, v40, v41
	v_cvt_pk_bf16_f32 v40, v30, v31
	v_cvt_pk_bf16_f32 v41, v32, v33
	global_store_dwordx4 v[156:157], v[38:41], off offset:256 nt
.Lepn0_dn:
	s_branch .LBB0_300
.LBB0_298:
	s_andn2_b64 vcc, exec, s[24:25]
	s_cbranch_vccnz .LBB0_300
	v_or_b32_e32 v32, 16, v152
	v_ashrrev_i32_e32 v153, 31, v152
	v_ashrrev_i32_e32 v33, 31, v32
	v_lshlrev_b64 v[30:31], 8, v[152:153]
	v_lshlrev_b64 v[32:33], 8, v[32:33]
	v_lshl_add_u64 v[30:31], v[146:147], 0, v[30:31]
	v_lshl_add_u64 v[32:33], v[146:147], 0, v[32:33]
	global_store_dwordx4 v[30:31], v[70:73], off
	global_store_dwordx4 v[30:31], v[66:69], off offset:16
	global_store_dwordx4 v[32:33], v[62:65], off
	global_store_dwordx4 v[32:33], v[58:61], off offset:16
	v_or_b32_e32 v32, 32, v152
	v_ashrrev_i32_e32 v33, 31, v32
	v_lshlrev_b64 v[32:33], 8, v[32:33]
	v_lshl_add_u64 v[32:33], v[146:147], 0, v[32:33]
	global_store_dwordx4 v[32:33], v[54:57], off
	global_store_dwordx4 v[32:33], v[50:53], off offset:16
	v_or_b32_e32 v32, 48, v152
	v_ashrrev_i32_e32 v33, 31, v32
	s_mov_b32 s2, 0x8000
	v_lshlrev_b64 v[32:33], 8, v[32:33]
	v_add_co_u32_e32 v38, vcc, s2, v30
	v_lshl_add_u64 v[32:33], v[146:147], 0, v[32:33]
	s_mov_b64 s[6:7], 0x8000
	v_addc_co_u32_e32 v39, vcc, 0, v31, vcc
	global_store_dwordx4 v[32:33], v[46:49], off
	global_store_dwordx4 v[32:33], v[42:45], off offset:16
	v_lshl_add_u64 v[32:33], v[30:31], 0, s[6:7]
	global_store_dwordx4 v[38:39], v[34:37], off
	global_store_dwordx4 v[32:33], v[26:29], off offset:16
	s_mov_b64 s[6:7], 0x9000
	s_nop 0
	v_add_co_u32_e32 v28, vcc, 0x9000, v30
	v_lshl_add_u64 v[26:27], v[30:31], 0, s[6:7]
	s_nop 0
	v_addc_co_u32_e32 v29, vcc, 0, v31, vcc
	global_store_dwordx4 v[28:29], v[22:25], off
	global_store_dwordx4 v[26:27], v[18:21], off offset:16
	s_mov_b64 s[6:7], 0xa000
	s_nop 0
	v_add_co_u32_e32 v20, vcc, 0xa000, v30
	v_lshl_add_u64 v[18:19], v[30:31], 0, s[6:7]
	s_nop 0
	v_addc_co_u32_e32 v21, vcc, 0, v31, vcc
	global_store_dwordx4 v[20:21], v[14:17], off
	global_store_dwordx4 v[18:19], v[10:13], off offset:16
	s_mov_b64 s[6:7], 0xb000
	s_nop 0
	v_add_co_u32_e32 v12, vcc, 0xb000, v30
	v_lshl_add_u64 v[10:11], v[30:31], 0, s[6:7]
	s_nop 0
	v_addc_co_u32_e32 v13, vcc, 0, v31, vcc
	global_store_dwordx4 v[12:13], v[6:9], off
	global_store_dwordx4 v[10:11], v[2:5], off offset:16

.LBB0_718:
	s_add_i32 s0, s4, 0xffffffbd
	s_cmpk_gt_i32 s4, 0x42
	s_cselect_b32 s5, 3, 0
	s_and_b64 s[6:7], s[6:7], exec
	s_cselect_b32 s5, 2, s5
	s_cmp_lt_u32 s0, -8
	s_cselect_b32 s0, s5, 1
	s_cmp_lg_u32 s0, 0
	s_cselect_b64 s[26:27], -1, 0
	s_cmp_eq_u32 s0, 3
	s_cselect_b64 s[6:7], -1, 0
	s_cmp_eq_u32 s0, 0
	s_cbranch_scc1 .Lepn1_m0
	s_and_b64 vcc, exec, s[6:7]
	s_cbranch_vccnz .Lepn1_m3
	v_lshl_or_b32 v158, s4, 8, v167
	v_mov_b64_e32 v[160:161], s[64:65]
	v_ashrrev_i32_e32 v159, 31, v158
	v_mad_i64_i32 v[160:161], s[4:5], v156, s49, v[160:161]
	v_lshl_add_u64 v[160:161], v[158:159], 1, v[160:161]
	s_lshl_b32 s98, s49, 4
	s_mov_b32 s99, 0
	s_mul_i32 s100, s49, 0x50
	s_mov_b32 s101, 0
	v_mov_b32_e32 v242, 0xbfb8aa3b
	s_waitcnt vmcnt(0)
	v_pk_mul_f32 v[234:235], v[66:67], v[242:243] op_sel_hi:[1,0]
	v_exp_f32_e32 v234, v234
	v_exp_f32_e32 v235, v235
	v_pk_mul_f32 v[236:237], v[68:69], v[242:243] op_sel_hi:[1,0]
	v_exp_f32_e32 v236, v236
	v_exp_f32_e32 v237, v237
	v_pk_mul_f32 v[238:239], v[70:71], v[242:243] op_sel_hi:[1,0]
	v_exp_f32_e32 v238, v238
	v_exp_f32_e32 v239, v239
	v_pk_mul_f32 v[240:241], v[72:73], v[242:243] op_sel_hi:[1,0]
	v_exp_f32_e32 v240, v240
	v_exp_f32_e32 v241, v241
	v_pk_add_f32 v[234:235], v[234:235], 1.0 op_sel_hi:[1,0]
	v_rcp_f32_e32 v234, v234
	v_rcp_f32_e32 v235, v235
	v_pk_add_f32 v[236:237], v[236:237], 1.0 op_sel_hi:[1,0]
	v_rcp_f32_e32 v236, v236
	v_rcp_f32_e32 v237, v237
	v_pk_add_f32 v[238:239], v[238:239], 1.0 op_sel_hi:[1,0]
	v_rcp_f32_e32 v238, v238
	v_rcp_f32_e32 v239, v239
	v_pk_add_f32 v[240:241], v[240:241], 1.0 op_sel_hi:[1,0]
	v_rcp_f32_e32 v240, v240
	v_rcp_f32_e32 v241, v241
	v_pk_mul_f32 v[66:67], v[66:67], v[234:235]
	v_pk_mul_f32 v[66:67], v[66:67], v[102:103]
	v_pk_mul_f32 v[68:69], v[68:69], v[236:237]
	v_pk_mul_f32 v[68:69], v[68:69], v[104:105]
	v_pk_mul_f32 v[70:71], v[70:71], v[238:239]
	v_pk_mul_f32 v[70:71], v[70:71], v[98:99]
	v_pk_mul_f32 v[72:73], v[72:73], v[240:241]
	v_pk_mul_f32 v[72:73], v[72:73], v[100:101]
	v_cvt_pk_bf16_f32 v70, v70, v71
	v_cvt_pk_bf16_f32 v71, v72, v73
	v_cvt_pk_bf16_f32 v72, v66, v67
	v_cvt_pk_bf16_f32 v73, v68, v69
	global_store_dwordx4 v[160:161], v[70:73], off nt
	v_pk_mul_f32 v[234:235], v[130:131], v[242:243] op_sel_hi:[1,0]
	v_exp_f32_e32 v234, v234
	v_exp_f32_e32 v235, v235
	v_pk_mul_f32 v[236:237], v[132:133], v[242:243] op_sel_hi:[1,0]
	v_exp_f32_e32 v236, v236
	v_exp_f32_e32 v237, v237
	v_pk_mul_f32 v[238:239], v[134:135], v[242:243] op_sel_hi:[1,0]
	v_exp_f32_e32 v238, v238
	v_exp_f32_e32 v239, v239
	v_pk_mul_f32 v[240:241], v[136:137], v[242:243] op_sel_hi:[1,0]
	v_exp_f32_e32 v240, v240
	v_exp_f32_e32 v241, v241
	v_pk_add_f32 v[234:235], v[234:235], 1.0 op_sel_hi:[1,0]
	v_rcp_f32_e32 v234, v234
	v_rcp_f32_e32 v235, v235
	v_pk_add_f32 v[236:237], v[236:237], 1.0 op_sel_hi:[1,0]
	v_rcp_f32_e32 v236, v236
	v_rcp_f32_e32 v237, v237
	v_pk_add_f32 v[238:239], v[238:239], 1.0 op_sel_hi:[1,0]
	v_rcp_f32_e32 v238, v238
	v_rcp_f32_e32 v239, v239
	v_pk_add_f32 v[240:241], v[240:241], 1.0 op_sel_hi:[1,0]
	v_rcp_f32_e32 v240, v240
	v_rcp_f32_e32 v241, v241
	v_pk_mul_f32 v[130:131], v[130:131], v[234:235]
	v_pk_mul_f32 v[130:131], v[130:131], v[102:103]
	v_pk_mul_f32 v[132:133], v[132:133], v[236:237]
	v_pk_mul_f32 v[132:133], v[132:133], v[104:105]
	v_pk_mul_f32 v[134:135], v[134:135], v[238:239]
	v_pk_mul_f32 v[134:135], v[134:135], v[98:99]
	v_pk_mul_f32 v[136:137], v[136:137], v[240:241]
	v_pk_mul_f32 v[136:137], v[136:137], v[100:101]
	v_cvt_pk_bf16_f32 v134, v134, v135
	v_cvt_pk_bf16_f32 v135, v136, v137
	v_cvt_pk_bf16_f32 v136, v130, v131
	v_cvt_pk_bf16_f32 v137, v132, v133
	global_store_dwordx4 v[160:161], v[134:137], off offset:256 nt
	v_lshl_add_u64 v[160:161], v[160:161], 0, s[98:99]
	v_pk_mul_f32 v[234:235], v[58:59], v[242:243] op_sel_hi:[1,0]
	v_exp_f32_e32 v234, v234
	v_exp_f32_e32 v235, v235
	v_pk_mul_f32 v[236:237], v[60:61], v[242:243] op_sel_hi:[1,0]
	v_exp_f32_e32 v236, v236
	v_exp_f32_e32 v237, v237
	v_pk_mul_f32 v[238:239], v[62:63], v[242:243] op_sel_hi:[1,0]
	v_exp_f32_e32 v238, v238
	v_exp_f32_e32 v239, v239
	v_pk_mul_f32 v[240:241], v[64:65], v[242:243] op_sel_hi:[1,0]
	v_exp_f32_e32 v240, v240
	v_exp_f32_e32 v241, v241
	v_pk_add_f32 v[234:235], v[234:235], 1.0 op_sel_hi:[1,0]
	v_rcp_f32_e32 v234, v234
	v_rcp_f32_e32 v235, v235
	v_pk_add_f32 v[236:237], v[236:237], 1.0 op_sel_hi:[1,0]
	v_rcp_f32_e32 v236, v236
	v_rcp_f32_e32 v237, v237
	v_pk_add_f32 v[238:239], v[238:239], 1.0 op_sel_hi:[1,0]
	v_rcp_f32_e32 v238, v238
	v_rcp_f32_e32 v239, v239
	v_pk_add_f32 v[240:241], v[240:241], 1.0 op_sel_hi:[1,0]
	v_rcp_f32_e32 v240, v240
	v_rcp_f32_e32 v241, v241
	v_pk_mul_f32 v[58:59], v[58:59], v[234:235]
	v_pk_mul_f32 v[58:59], v[58:59], v[102:103]
	v_pk_mul_f32 v[60:61], v[60:61], v[236:237]
	v_pk_mul_f32 v[60:61], v[60:61], v[104:105]
	v_pk_mul_f32 v[62:63], v[62:63], v[238:239]
	v_pk_mul_f32 v[62:63], v[62:63], v[98:99]
	v_pk_mul_f32 v[64:65], v[64:65], v[240:241]
	v_pk_mul_f32 v[64:65], v[64:65], v[100:101]
	v_cvt_pk_bf16_f32 v62, v62, v63
	v_cvt_pk_bf16_f32 v63, v64, v65
	v_cvt_pk_bf16_f32 v64, v58, v59
	v_cvt_pk_bf16_f32 v65, v60, v61
	global_store_dwordx4 v[160:161], v[62:65], off nt
	v_pk_mul_f32 v[234:235], v[122:123], v[242:243] op_sel_hi:[1,0]
	v_exp_f32_e32 v234, v234
	v_exp_f32_e32 v235, v235
	v_pk_mul_f32 v[236:237], v[124:125], v[242:243] op_sel_hi:[1,0]
	v_exp_f32_e32 v236, v236
	v_exp_f32_e32 v237, v237
	v_pk_mul_f32 v[238:239], v[126:127], v[242:243] op_sel_hi:[1,0]
	v_exp_f32_e32 v238, v238
	v_exp_f32_e32 v239, v239
	v_pk_mul_f32 v[240:241], v[128:129], v[242:243] op_sel_hi:[1,0]
	v_exp_f32_e32 v240, v240
	v_exp_f32_e32 v241, v241
	v_pk_add_f32 v[234:235], v[234:235], 1.0 op_sel_hi:[1,0]
	v_rcp_f32_e32 v234, v234
	v_rcp_f32_e32 v235, v235
	v_pk_add_f32 v[236:237], v[236:237], 1.0 op_sel_hi:[1,0]
	v_rcp_f32_e32 v236, v236
	v_rcp_f32_e32 v237, v237
	v_pk_add_f32 v[238:239], v[238:239], 1.0 op_sel_hi:[1,0]
	v_rcp_f32_e32 v238, v238
	v_rcp_f32_e32 v239, v239
	v_pk_add_f32 v[240:241], v[240:241], 1.0 op_sel_hi:[1,0]
	v_rcp_f32_e32 v240, v240
	v_rcp_f32_e32 v241, v241
	v_pk_mul_f32 v[122:123], v[122:123], v[234:235]
	v_pk_mul_f32 v[122:123], v[122:123], v[102:103]
	v_pk_mul_f32 v[124:125], v[124:125], v[236:237]
	v_pk_mul_f32 v[124:125], v[124:125], v[104:105]
	v_pk_mul_f32 v[126:127], v[126:127], v[238:239]
	v_pk_mul_f32 v[126:127], v[126:127], v[98:99]
	v_pk_mul_f32 v[128:129], v[128:129], v[240:241]
	v_pk_mul_f32 v[128:129], v[128:129], v[100:101]
	v_cvt_pk_bf16_f32 v126, v126, v127
	v_cvt_pk_bf16_f32 v127, v128, v129
	v_cvt_pk_bf16_f32 v128, v122, v123
	v_cvt_pk_bf16_f32 v129, v124, v125
	global_store_dwordx4 v[160:161], v[126:129], off offset:256 nt
	v_lshl_add_u64 v[160:161], v[160:161], 0, s[98:99]
	v_pk_mul_f32 v[234:235], v[50:51], v[242:243] op_sel_hi:[1,0]
	v_exp_f32_e32 v234, v234
	v_exp_f32_e32 v235, v235
	v_pk_mul_f32 v[236:237], v[52:53], v[242:243] op_sel_hi:[1,0]
	v_exp_f32_e32 v236, v236
	v_exp_f32_e32 v237, v237
	v_pk_mul_f32 v[238:239], v[54:55], v[242:243] op_sel_hi:[1,0]
	v_exp_f32_e32 v238, v238
	v_exp_f32_e32 v239, v239
	v_pk_mul_f32 v[240:241], v[56:57], v[242:243] op_sel_hi:[1,0]
	v_exp_f32_e32 v240, v240
	v_exp_f32_e32 v241, v241
	v_pk_add_f32 v[234:235], v[234:235], 1.0 op_sel_hi:[1,0]
	v_rcp_f32_e32 v234, v234
	v_rcp_f32_e32 v235, v235
	v_pk_add_f32 v[236:237], v[236:237], 1.0 op_sel_hi:[1,0]
	v_rcp_f32_e32 v236, v236
	v_rcp_f32_e32 v237, v237
	v_pk_add_f32 v[238:239], v[238:239], 1.0 op_sel_hi:[1,0]
	v_rcp_f32_e32 v238, v238
	v_rcp_f32_e32 v239, v239
	v_pk_add_f32 v[240:241], v[240:241], 1.0 op_sel_hi:[1,0]
	v_rcp_f32_e32 v240, v240
	v_rcp_f32_e32 v241, v241
	v_pk_mul_f32 v[50:51], v[50:51], v[234:235]
	v_pk_mul_f32 v[50:51], v[50:51], v[102:103]
	v_pk_mul_f32 v[52:53], v[52:53], v[236:237]
	v_pk_mul_f32 v[52:53], v[52:53], v[104:105]
	v_pk_mul_f32 v[54:55], v[54:55], v[238:239]
	v_pk_mul_f32 v[54:55], v[54:55], v[98:99]
	v_pk_mul_f32 v[56:57], v[56:57], v[240:241]
	v_pk_mul_f32 v[56:57], v[56:57], v[100:101]
	v_cvt_pk_bf16_f32 v54, v54, v55
	v_cvt_pk_bf16_f32 v55, v56, v57
	v_cvt_pk_bf16_f32 v56, v50, v51
	v_cvt_pk_bf16_f32 v57, v52, v53
	global_store_dwordx4 v[160:161], v[54:57], off nt
	v_pk_mul_f32 v[234:235], v[114:115], v[242:243] op_sel_hi:[1,0]
	v_exp_f32_e32 v234, v234
	v_exp_f32_e32 v235, v235
	v_pk_mul_f32 v[236:237], v[116:117], v[242:243] op_sel_hi:[1,0]
	v_exp_f32_e32 v236, v236
	v_exp_f32_e32 v237, v237
	v_pk_mul_f32 v[238:239], v[118:119], v[242:243] op_sel_hi:[1,0]
	v_exp_f32_e32 v238, v238
	v_exp_f32_e32 v239, v239
	v_pk_mul_f32 v[240:241], v[120:121], v[242:243] op_sel_hi:[1,0]
	v_exp_f32_e32 v240, v240
	v_exp_f32_e32 v241, v241
	v_pk_add_f32 v[234:235], v[234:235], 1.0 op_sel_hi:[1,0]
	v_rcp_f32_e32 v234, v234
	v_rcp_f32_e32 v235, v235
	v_pk_add_f32 v[236:237], v[236:237], 1.0 op_sel_hi:[1,0]
	v_rcp_f32_e32 v236, v236
	v_rcp_f32_e32 v237, v237
	v_pk_add_f32 v[238:239], v[238:239], 1.0 op_sel_hi:[1,0]
	v_rcp_f32_e32 v238, v238
	v_rcp_f32_e32 v239, v239
	v_pk_add_f32 v[240:241], v[240:241], 1.0 op_sel_hi:[1,0]
	v_rcp_f32_e32 v240, v240
	v_rcp_f32_e32 v241, v241
	v_pk_mul_f32 v[114:115], v[114:115], v[234:235]
	v_pk_mul_f32 v[114:115], v[114:115], v[102:103]
	v_pk_mul_f32 v[116:117], v[116:117], v[236:237]
	v_pk_mul_f32 v[116:117], v[116:117], v[104:105]
	v_pk_mul_f32 v[118:119], v[118:119], v[238:239]
	v_pk_mul_f32 v[118:119], v[118:119], v[98:99]
	v_pk_mul_f32 v[120:121], v[120:121], v[240:241]
	v_pk_mul_f32 v[120:121], v[120:121], v[100:101]
	v_cvt_pk_bf16_f32 v118, v118, v119
	v_cvt_pk_bf16_f32 v119, v120, v121
	v_cvt_pk_bf16_f32 v120, v114, v115
	v_cvt_pk_bf16_f32 v121, v116, v117
	global_store_dwordx4 v[160:161], v[118:121], off offset:256 nt
	v_lshl_add_u64 v[160:161], v[160:161], 0, s[98:99]
	v_pk_mul_f32 v[234:235], v[42:43], v[242:243] op_sel_hi:[1,0]
	v_exp_f32_e32 v234, v234
	v_exp_f32_e32 v235, v235
	v_pk_mul_f32 v[236:237], v[44:45], v[242:243] op_sel_hi:[1,0]
	v_exp_f32_e32 v236, v236
	v_exp_f32_e32 v237, v237
	v_pk_mul_f32 v[238:239], v[46:47], v[242:243] op_sel_hi:[1,0]
	v_exp_f32_e32 v238, v238
	v_exp_f32_e32 v239, v239
	v_pk_mul_f32 v[240:241], v[48:49], v[242:243] op_sel_hi:[1,0]
	v_exp_f32_e32 v240, v240
	v_exp_f32_e32 v241, v241
	v_pk_add_f32 v[234:235], v[234:235], 1.0 op_sel_hi:[1,0]
	v_rcp_f32_e32 v234, v234
	v_rcp_f32_e32 v235, v235
	v_pk_add_f32 v[236:237], v[236:237], 1.0 op_sel_hi:[1,0]
	v_rcp_f32_e32 v236, v236
	v_rcp_f32_e32 v237, v237
	v_pk_add_f32 v[238:239], v[238:239], 1.0 op_sel_hi:[1,0]
	v_rcp_f32_e32 v238, v238
	v_rcp_f32_e32 v239, v239
	v_pk_add_f32 v[240:241], v[240:241], 1.0 op_sel_hi:[1,0]
	v_rcp_f32_e32 v240, v240
	v_rcp_f32_e32 v241, v241
	v_pk_mul_f32 v[42:43], v[42:43], v[234:235]
	v_pk_mul_f32 v[42:43], v[42:43], v[102:103]
	v_pk_mul_f32 v[44:45], v[44:45], v[236:237]
	v_pk_mul_f32 v[44:45], v[44:45], v[104:105]
	v_pk_mul_f32 v[46:47], v[46:47], v[238:239]
	v_pk_mul_f32 v[46:47], v[46:47], v[98:99]
	v_pk_mul_f32 v[48:49], v[48:49], v[240:241]
	v_pk_mul_f32 v[48:49], v[48:49], v[100:101]
	v_cvt_pk_bf16_f32 v46, v46, v47
	v_cvt_pk_bf16_f32 v47, v48, v49
	v_cvt_pk_bf16_f32 v48, v42, v43
	v_cvt_pk_bf16_f32 v49, v44, v45
	global_store_dwordx4 v[160:161], v[46:49], off nt
	v_pk_mul_f32 v[234:235], v[106:107], v[242:243] op_sel_hi:[1,0]
	v_exp_f32_e32 v234, v234
	v_exp_f32_e32 v235, v235
	v_pk_mul_f32 v[236:237], v[108:109], v[242:243] op_sel_hi:[1,0]
	v_exp_f32_e32 v236, v236
	v_exp_f32_e32 v237, v237
	v_pk_mul_f32 v[238:239], v[110:111], v[242:243] op_sel_hi:[1,0]
	v_exp_f32_e32 v238, v238
	v_exp_f32_e32 v239, v239
	v_pk_mul_f32 v[240:241], v[112:113], v[242:243] op_sel_hi:[1,0]
	v_exp_f32_e32 v240, v240
	v_exp_f32_e32 v241, v241
	v_pk_add_f32 v[234:235], v[234:235], 1.0 op_sel_hi:[1,0]
	v_rcp_f32_e32 v234, v234
	v_rcp_f32_e32 v235, v235
	v_pk_add_f32 v[236:237], v[236:237], 1.0 op_sel_hi:[1,0]
	v_rcp_f32_e32 v236, v236
	v_rcp_f32_e32 v237, v237
	v_pk_add_f32 v[238:239], v[238:239], 1.0 op_sel_hi:[1,0]
	v_rcp_f32_e32 v238, v238
	v_rcp_f32_e32 v239, v239
	v_pk_add_f32 v[240:241], v[240:241], 1.0 op_sel_hi:[1,0]
	v_rcp_f32_e32 v240, v240
	v_rcp_f32_e32 v241, v241
	v_pk_mul_f32 v[106:107], v[106:107], v[234:235]
	v_pk_mul_f32 v[106:107], v[106:107], v[102:103]
	v_pk_mul_f32 v[108:109], v[108:109], v[236:237]
	v_pk_mul_f32 v[108:109], v[108:109], v[104:105]
	v_pk_mul_f32 v[110:111], v[110:111], v[238:239]
	v_pk_mul_f32 v[110:111], v[110:111], v[98:99]
	v_pk_mul_f32 v[112:113], v[112:113], v[240:241]
	v_pk_mul_f32 v[112:113], v[112:113], v[100:101]
	v_cvt_pk_bf16_f32 v110, v110, v111
	v_cvt_pk_bf16_f32 v111, v112, v113
	v_cvt_pk_bf16_f32 v112, v106, v107
	v_cvt_pk_bf16_f32 v113, v108, v109
	global_store_dwordx4 v[160:161], v[110:113], off offset:256 nt
	v_lshl_add_u64 v[160:161], v[160:161], 0, s[100:101]
	v_pk_mul_f32 v[234:235], v[26:27], v[242:243] op_sel_hi:[1,0]
	v_exp_f32_e32 v234, v234
	v_exp_f32_e32 v235, v235
	v_pk_mul_f32 v[236:237], v[28:29], v[242:243] op_sel_hi:[1,0]
	v_exp_f32_e32 v236, v236
	v_exp_f32_e32 v237, v237
	v_pk_mul_f32 v[238:239], v[34:35], v[242:243] op_sel_hi:[1,0]
	v_exp_f32_e32 v238, v238
	v_exp_f32_e32 v239, v239
	v_pk_mul_f32 v[240:241], v[36:37], v[242:243] op_sel_hi:[1,0]
	v_exp_f32_e32 v240, v240
	v_exp_f32_e32 v241, v241
	v_pk_add_f32 v[234:235], v[234:235], 1.0 op_sel_hi:[1,0]
	v_rcp_f32_e32 v234, v234
	v_rcp_f32_e32 v235, v235
	v_pk_add_f32 v[236:237], v[236:237], 1.0 op_sel_hi:[1,0]
	v_rcp_f32_e32 v236, v236
	v_rcp_f32_e32 v237, v237
	v_pk_add_f32 v[238:239], v[238:239], 1.0 op_sel_hi:[1,0]
	v_rcp_f32_e32 v238, v238
	v_rcp_f32_e32 v239, v239
	v_pk_add_f32 v[240:241], v[240:241], 1.0 op_sel_hi:[1,0]
	v_rcp_f32_e32 v240, v240
	v_rcp_f32_e32 v241, v241
	v_pk_mul_f32 v[26:27], v[26:27], v[234:235]
	v_pk_mul_f32 v[26:27], v[26:27], v[102:103]
	v_pk_mul_f32 v[28:29], v[28:29], v[236:237]
	v_pk_mul_f32 v[28:29], v[28:29], v[104:105]
	v_pk_mul_f32 v[34:35], v[34:35], v[238:239]
	v_pk_mul_f32 v[34:35], v[34:35], v[98:99]
	v_pk_mul_f32 v[36:37], v[36:37], v[240:241]
	v_pk_mul_f32 v[36:37], v[36:37], v[100:101]
	v_cvt_pk_bf16_f32 v34, v34, v35
	v_cvt_pk_bf16_f32 v35, v36, v37
	v_cvt_pk_bf16_f32 v36, v26, v27
	v_cvt_pk_bf16_f32 v37, v28, v29
	global_store_dwordx4 v[160:161], v[34:37], off nt
	v_pk_mul_f32 v[234:235], v[90:91], v[242:243] op_sel_hi:[1,0]
	v_exp_f32_e32 v234, v234
	v_exp_f32_e32 v235, v235
	v_pk_mul_f32 v[236:237], v[92:93], v[242:243] op_sel_hi:[1,0]
	v_exp_f32_e32 v236, v236
	v_exp_f32_e32 v237, v237
	v_pk_mul_f32 v[238:239], v[94:95], v[242:243] op_sel_hi:[1,0]
	v_exp_f32_e32 v238, v238
	v_exp_f32_e32 v239, v239
	v_pk_mul_f32 v[240:241], v[96:97], v[242:243] op_sel_hi:[1,0]
	v_exp_f32_e32 v240, v240
	v_exp_f32_e32 v241, v241
	v_pk_add_f32 v[234:235], v[234:235], 1.0 op_sel_hi:[1,0]
	v_rcp_f32_e32 v234, v234
	v_rcp_f32_e32 v235, v235
	v_pk_add_f32 v[236:237], v[236:237], 1.0 op_sel_hi:[1,0]
	v_rcp_f32_e32 v236, v236
	v_rcp_f32_e32 v237, v237
	v_pk_add_f32 v[238:239], v[238:239], 1.0 op_sel_hi:[1,0]
	v_rcp_f32_e32 v238, v238
	v_rcp_f32_e32 v239, v239
	v_pk_add_f32 v[240:241], v[240:241], 1.0 op_sel_hi:[1,0]
	v_rcp_f32_e32 v240, v240
	v_rcp_f32_e32 v241, v241
	v_pk_mul_f32 v[90:91], v[90:91], v[234:235]
	v_pk_mul_f32 v[90:91], v[90:91], v[102:103]
	v_pk_mul_f32 v[92:93], v[92:93], v[236:237]
	v_pk_mul_f32 v[92:93], v[92:93], v[104:105]
	v_pk_mul_f32 v[94:95], v[94:95], v[238:239]
	v_pk_mul_f32 v[94:95], v[94:95], v[98:99]
	v_pk_mul_f32 v[96:97], v[96:97], v[240:241]
	v_pk_mul_f32 v[96:97], v[96:97], v[100:101]
	v_cvt_pk_bf16_f32 v94, v94, v95
	v_cvt_pk_bf16_f32 v95, v96, v97
	v_cvt_pk_bf16_f32 v96, v90, v91
	v_cvt_pk_bf16_f32 v97, v92, v93
	global_store_dwordx4 v[160:161], v[94:97], off offset:256 nt
	v_lshl_add_u64 v[160:161], v[160:161], 0, s[98:99]
	v_pk_mul_f32 v[234:235], v[18:19], v[242:243] op_sel_hi:[1,0]
	v_exp_f32_e32 v234, v234
	v_exp_f32_e32 v235, v235
	v_pk_mul_f32 v[236:237], v[20:21], v[242:243] op_sel_hi:[1,0]
	v_exp_f32_e32 v236, v236
	v_exp_f32_e32 v237, v237
	v_pk_mul_f32 v[238:239], v[22:23], v[242:243] op_sel_hi:[1,0]
	v_exp_f32_e32 v238, v238
	v_exp_f32_e32 v239, v239
	v_pk_mul_f32 v[240:241], v[24:25], v[242:243] op_sel_hi:[1,0]
	v_exp_f32_e32 v240, v240
	v_exp_f32_e32 v241, v241
	v_pk_add_f32 v[234:235], v[234:235], 1.0 op_sel_hi:[1,0]
	v_rcp_f32_e32 v234, v234
	v_rcp_f32_e32 v235, v235
	v_pk_add_f32 v[236:237], v[236:237], 1.0 op_sel_hi:[1,0]
	v_rcp_f32_e32 v236, v236
	v_rcp_f32_e32 v237, v237
	v_pk_add_f32 v[238:239], v[238:239], 1.0 op_sel_hi:[1,0]
	v_rcp_f32_e32 v238, v238
	v_rcp_f32_e32 v239, v239
	v_pk_add_f32 v[240:241], v[240:241], 1.0 op_sel_hi:[1,0]
	v_rcp_f32_e32 v240, v240
	v_rcp_f32_e32 v241, v241
	v_pk_mul_f32 v[18:19], v[18:19], v[234:235]
	v_pk_mul_f32 v[18:19], v[18:19], v[102:103]
	v_pk_mul_f32 v[20:21], v[20:21], v[236:237]
	v_pk_mul_f32 v[20:21], v[20:21], v[104:105]
	v_pk_mul_f32 v[22:23], v[22:23], v[238:239]
	v_pk_mul_f32 v[22:23], v[22:23], v[98:99]
	v_pk_mul_f32 v[24:25], v[24:25], v[240:241]
	v_pk_mul_f32 v[24:25], v[24:25], v[100:101]
	v_cvt_pk_bf16_f32 v22, v22, v23
	v_cvt_pk_bf16_f32 v23, v24, v25
	v_cvt_pk_bf16_f32 v24, v18, v19
	v_cvt_pk_bf16_f32 v25, v20, v21
	global_store_dwordx4 v[160:161], v[22:25], off nt
	v_pk_mul_f32 v[234:235], v[82:83], v[242:243] op_sel_hi:[1,0]
	v_exp_f32_e32 v234, v234
	v_exp_f32_e32 v235, v235
	v_pk_mul_f32 v[236:237], v[84:85], v[242:243] op_sel_hi:[1,0]
	v_exp_f32_e32 v236, v236
	v_exp_f32_e32 v237, v237
	v_pk_mul_f32 v[238:239], v[86:87], v[242:243] op_sel_hi:[1,0]
	v_exp_f32_e32 v238, v238
	v_exp_f32_e32 v239, v239
	v_pk_mul_f32 v[240:241], v[88:89], v[242:243] op_sel_hi:[1,0]
	v_exp_f32_e32 v240, v240
	v_exp_f32_e32 v241, v241
	v_pk_add_f32 v[234:235], v[234:235], 1.0 op_sel_hi:[1,0]
	v_rcp_f32_e32 v234, v234
	v_rcp_f32_e32 v235, v235
	v_pk_add_f32 v[236:237], v[236:237], 1.0 op_sel_hi:[1,0]
	v_rcp_f32_e32 v236, v236
	v_rcp_f32_e32 v237, v237
	v_pk_add_f32 v[238:239], v[238:239], 1.0 op_sel_hi:[1,0]
	v_rcp_f32_e32 v238, v238
	v_rcp_f32_e32 v239, v239
	v_pk_add_f32 v[240:241], v[240:241], 1.0 op_sel_hi:[1,0]
	v_rcp_f32_e32 v240, v240
	v_rcp_f32_e32 v241, v241
	v_pk_mul_f32 v[82:83], v[82:83], v[234:235]
	v_pk_mul_f32 v[82:83], v[82:83], v[102:103]
	v_pk_mul_f32 v[84:85], v[84:85], v[236:237]
	v_pk_mul_f32 v[84:85], v[84:85], v[104:105]
	v_pk_mul_f32 v[86:87], v[86:87], v[238:239]
	v_pk_mul_f32 v[86:87], v[86:87], v[98:99]
	v_pk_mul_f32 v[88:89], v[88:89], v[240:241]
	v_pk_mul_f32 v[88:89], v[88:89], v[100:101]
	v_cvt_pk_bf16_f32 v86, v86, v87
	v_cvt_pk_bf16_f32 v87, v88, v89
	v_cvt_pk_bf16_f32 v88, v82, v83
	v_cvt_pk_bf16_f32 v89, v84, v85
	global_store_dwordx4 v[160:161], v[86:89], off offset:256 nt
	v_lshl_add_u64 v[160:161], v[160:161], 0, s[98:99]
	v_pk_mul_f32 v[234:235], v[10:11], v[242:243] op_sel_hi:[1,0]
	v_exp_f32_e32 v234, v234
	v_exp_f32_e32 v235, v235
	v_pk_mul_f32 v[236:237], v[12:13], v[242:243] op_sel_hi:[1,0]
	v_exp_f32_e32 v236, v236
	v_exp_f32_e32 v237, v237
	v_pk_mul_f32 v[238:239], v[14:15], v[242:243] op_sel_hi:[1,0]
	v_exp_f32_e32 v238, v238
	v_exp_f32_e32 v239, v239
	v_pk_mul_f32 v[240:241], v[16:17], v[242:243] op_sel_hi:[1,0]
	v_exp_f32_e32 v240, v240
	v_exp_f32_e32 v241, v241
	v_pk_add_f32 v[234:235], v[234:235], 1.0 op_sel_hi:[1,0]
	v_rcp_f32_e32 v234, v234
	v_rcp_f32_e32 v235, v235
	v_pk_add_f32 v[236:237], v[236:237], 1.0 op_sel_hi:[1,0]
	v_rcp_f32_e32 v236, v236
	v_rcp_f32_e32 v237, v237
	v_pk_add_f32 v[238:239], v[238:239], 1.0 op_sel_hi:[1,0]
	v_rcp_f32_e32 v238, v238
	v_rcp_f32_e32 v239, v239
	v_pk_add_f32 v[240:241], v[240:241], 1.0 op_sel_hi:[1,0]
	v_rcp_f32_e32 v240, v240
	v_rcp_f32_e32 v241, v241
	v_pk_mul_f32 v[10:11], v[10:11], v[234:235]
	v_pk_mul_f32 v[10:11], v[10:11], v[102:103]
	v_pk_mul_f32 v[12:13], v[12:13], v[236:237]
	v_pk_mul_f32 v[12:13], v[12:13], v[104:105]
	v_pk_mul_f32 v[14:15], v[14:15], v[238:239]
	v_pk_mul_f32 v[14:15], v[14:15], v[98:99]
	v_pk_mul_f32 v[16:17], v[16:17], v[240:241]
	v_pk_mul_f32 v[16:17], v[16:17], v[100:101]
	v_cvt_pk_bf16_f32 v14, v14, v15
	v_cvt_pk_bf16_f32 v15, v16, v17
	v_cvt_pk_bf16_f32 v16, v10, v11
	v_cvt_pk_bf16_f32 v17, v12, v13
	global_store_dwordx4 v[160:161], v[14:17], off nt
	v_pk_mul_f32 v[234:235], v[74:75], v[242:243] op_sel_hi:[1,0]
	v_exp_f32_e32 v234, v234
	v_exp_f32_e32 v235, v235
	v_pk_mul_f32 v[236:237], v[76:77], v[242:243] op_sel_hi:[1,0]
	v_exp_f32_e32 v236, v236
	v_exp_f32_e32 v237, v237
	v_pk_mul_f32 v[238:239], v[78:79], v[242:243] op_sel_hi:[1,0]
	v_exp_f32_e32 v238, v238
	v_exp_f32_e32 v239, v239
	v_pk_mul_f32 v[240:241], v[80:81], v[242:243] op_sel_hi:[1,0]
	v_exp_f32_e32 v240, v240
	v_exp_f32_e32 v241, v241
	v_pk_add_f32 v[234:235], v[234:235], 1.0 op_sel_hi:[1,0]
	v_rcp_f32_e32 v234, v234
	v_rcp_f32_e32 v235, v235
	v_pk_add_f32 v[236:237], v[236:237], 1.0 op_sel_hi:[1,0]
	v_rcp_f32_e32 v236, v236
	v_rcp_f32_e32 v237, v237
	v_pk_add_f32 v[238:239], v[238:239], 1.0 op_sel_hi:[1,0]
	v_rcp_f32_e32 v238, v238
	v_rcp_f32_e32 v239, v239
	v_pk_add_f32 v[240:241], v[240:241], 1.0 op_sel_hi:[1,0]
	v_rcp_f32_e32 v240, v240
	v_rcp_f32_e32 v241, v241
	v_pk_mul_f32 v[74:75], v[74:75], v[234:235]
	v_pk_mul_f32 v[74:75], v[74:75], v[102:103]
	v_pk_mul_f32 v[76:77], v[76:77], v[236:237]
	v_pk_mul_f32 v[76:77], v[76:77], v[104:105]
	v_pk_mul_f32 v[78:79], v[78:79], v[238:239]
	v_pk_mul_f32 v[78:79], v[78:79], v[98:99]
	v_pk_mul_f32 v[80:81], v[80:81], v[240:241]
	v_pk_mul_f32 v[80:81], v[80:81], v[100:101]
	v_cvt_pk_bf16_f32 v78, v78, v79
	v_cvt_pk_bf16_f32 v79, v80, v81
	v_cvt_pk_bf16_f32 v80, v74, v75
	v_cvt_pk_bf16_f32 v81, v76, v77
	global_store_dwordx4 v[160:161], v[78:81], off offset:256 nt
	v_lshl_add_u64 v[160:161], v[160:161], 0, s[98:99]
	v_pk_mul_f32 v[234:235], v[2:3], v[242:243] op_sel_hi:[1,0]
	v_exp_f32_e32 v234, v234
	v_exp_f32_e32 v235, v235
	v_pk_mul_f32 v[236:237], v[4:5], v[242:243] op_sel_hi:[1,0]
	v_exp_f32_e32 v236, v236
	v_exp_f32_e32 v237, v237
	v_pk_mul_f32 v[238:239], v[6:7], v[242:243] op_sel_hi:[1,0]
	v_exp_f32_e32 v238, v238
	v_exp_f32_e32 v239, v239
	v_pk_mul_f32 v[240:241], v[8:9], v[242:243] op_sel_hi:[1,0]
	v_exp_f32_e32 v240, v240
	v_exp_f32_e32 v241, v241
	v_pk_add_f32 v[234:235], v[234:235], 1.0 op_sel_hi:[1,0]
	v_rcp_f32_e32 v234, v234
	v_rcp_f32_e32 v235, v235
	v_pk_add_f32 v[236:237], v[236:237], 1.0 op_sel_hi:[1,0]
	v_rcp_f32_e32 v236, v236
	v_rcp_f32_e32 v237, v237
	v_pk_add_f32 v[238:239], v[238:239], 1.0 op_sel_hi:[1,0]
	v_rcp_f32_e32 v238, v238
	v_rcp_f32_e32 v239, v239
	v_pk_add_f32 v[240:241], v[240:241], 1.0 op_sel_hi:[1,0]
	v_rcp_f32_e32 v240, v240
	v_rcp_f32_e32 v241, v241
	v_pk_mul_f32 v[2:3], v[2:3], v[234:235]
	v_pk_mul_f32 v[2:3], v[2:3], v[102:103]
	v_pk_mul_f32 v[4:5], v[4:5], v[236:237]
	v_pk_mul_f32 v[4:5], v[4:5], v[104:105]
	v_pk_mul_f32 v[6:7], v[6:7], v[238:239]
	v_pk_mul_f32 v[6:7], v[6:7], v[98:99]
	v_pk_mul_f32 v[8:9], v[8:9], v[240:241]
	v_pk_mul_f32 v[8:9], v[8:9], v[100:101]
	v_cvt_pk_bf16_f32 v6, v6, v7
	v_cvt_pk_bf16_f32 v7, v8, v9
	v_cvt_pk_bf16_f32 v8, v2, v3
	v_cvt_pk_bf16_f32 v9, v4, v5
	global_store_dwordx4 v[160:161], v[6:9], off nt
	v_pk_mul_f32 v[234:235], v[30:31], v[242:243] op_sel_hi:[1,0]
	v_exp_f32_e32 v234, v234
	v_exp_f32_e32 v235, v235
	v_pk_mul_f32 v[236:237], v[32:33], v[242:243] op_sel_hi:[1,0]
	v_exp_f32_e32 v236, v236
	v_exp_f32_e32 v237, v237
	v_pk_mul_f32 v[238:239], v[38:39], v[242:243] op_sel_hi:[1,0]
	v_exp_f32_e32 v238, v238
	v_exp_f32_e32 v239, v239
	v_pk_mul_f32 v[240:241], v[40:41], v[242:243] op_sel_hi:[1,0]
	v_exp_f32_e32 v240, v240
	v_exp_f32_e32 v241, v241
	v_pk_add_f32 v[234:235], v[234:235], 1.0 op_sel_hi:[1,0]
	v_rcp_f32_e32 v234, v234
	v_rcp_f32_e32 v235, v235
	v_pk_add_f32 v[236:237], v[236:237], 1.0 op_sel_hi:[1,0]
	v_rcp_f32_e32 v236, v236
	v_rcp_f32_e32 v237, v237
	v_pk_add_f32 v[238:239], v[238:239], 1.0 op_sel_hi:[1,0]
	v_rcp_f32_e32 v238, v238
	v_rcp_f32_e32 v239, v239
	v_pk_add_f32 v[240:241], v[240:241], 1.0 op_sel_hi:[1,0]
	v_rcp_f32_e32 v240, v240
	v_rcp_f32_e32 v241, v241
	v_pk_mul_f32 v[30:31], v[30:31], v[234:235]
	v_pk_mul_f32 v[30:31], v[30:31], v[102:103]
	v_pk_mul_f32 v[32:33], v[32:33], v[236:237]
	v_pk_mul_f32 v[32:33], v[32:33], v[104:105]
	v_pk_mul_f32 v[38:39], v[38:39], v[238:239]
	v_pk_mul_f32 v[38:39], v[38:39], v[98:99]
	v_pk_mul_f32 v[40:41], v[40:41], v[240:241]
	v_pk_mul_f32 v[40:41], v[40:41], v[100:101]
	v_cvt_pk_bf16_f32 v38, v38, v39
	v_cvt_pk_bf16_f32 v39, v40, v41
	v_cvt_pk_bf16_f32 v40, v30, v31
	v_cvt_pk_bf16_f32 v41, v32, v33
	global_store_dwordx4 v[160:161], v[38:41], off offset:256 nt
	s_branch .Lepn1_dn
.Lepn1_m3:
	v_lshl_or_b32 v158, s4, 8, v167
	v_mov_b64_e32 v[160:161], s[64:65]
	v_ashrrev_i32_e32 v159, 31, v158
	v_mad_i64_i32 v[160:161], s[4:5], v156, s49, v[160:161]
	v_lshl_add_u64 v[160:161], v[158:159], 1, v[160:161]
	s_lshl_b32 s98, s49, 4
	s_mov_b32 s99, 0
	s_mul_i32 s100, s49, 0x50
	s_mov_b32 s101, 0
	v_mov_b32_e32 v242, 0xbfb8aa3b
	v_pk_mul_f32 v[234:235], v[66:67], v[242:243] op_sel_hi:[1,0]
	v_exp_f32_e32 v234, v234
	v_exp_f32_e32 v235, v235
	v_pk_mul_f32 v[236:237], v[68:69], v[242:243] op_sel_hi:[1,0]
	v_exp_f32_e32 v236, v236
	v_exp_f32_e32 v237, v237
	v_pk_mul_f32 v[238:239], v[70:71], v[242:243] op_sel_hi:[1,0]
	v_exp_f32_e32 v238, v238
	v_exp_f32_e32 v239, v239
	v_pk_mul_f32 v[240:241], v[72:73], v[242:243] op_sel_hi:[1,0]
	v_exp_f32_e32 v240, v240
	v_exp_f32_e32 v241, v241
	v_pk_add_f32 v[234:235], v[234:235], 1.0 op_sel_hi:[1,0]
	v_rcp_f32_e32 v234, v234
	v_rcp_f32_e32 v235, v235
	v_pk_add_f32 v[236:237], v[236:237], 1.0 op_sel_hi:[1,0]
	v_rcp_f32_e32 v236, v236
	v_rcp_f32_e32 v237, v237
	v_pk_add_f32 v[238:239], v[238:239], 1.0 op_sel_hi:[1,0]
	v_rcp_f32_e32 v238, v238
	v_rcp_f32_e32 v239, v239
	v_pk_add_f32 v[240:241], v[240:241], 1.0 op_sel_hi:[1,0]
	v_rcp_f32_e32 v240, v240
	v_rcp_f32_e32 v241, v241
	v_cvt_pk_bf16_f32 v70, v238, v239
	v_cvt_pk_bf16_f32 v71, v240, v241
	v_cvt_pk_bf16_f32 v72, v234, v235
	v_cvt_pk_bf16_f32 v73, v236, v237
	global_store_dwordx4 v[160:161], v[70:73], off nt
	v_pk_mul_f32 v[234:235], v[130:131], v[242:243] op_sel_hi:[1,0]
	v_exp_f32_e32 v234, v234
	v_exp_f32_e32 v235, v235
	v_pk_mul_f32 v[236:237], v[132:133], v[242:243] op_sel_hi:[1,0]
	v_exp_f32_e32 v236, v236
	v_exp_f32_e32 v237, v237
	v_pk_mul_f32 v[238:239], v[134:135], v[242:243] op_sel_hi:[1,0]
	v_exp_f32_e32 v238, v238
	v_exp_f32_e32 v239, v239
	v_pk_mul_f32 v[240:241], v[136:137], v[242:243] op_sel_hi:[1,0]
	v_exp_f32_e32 v240, v240
	v_exp_f32_e32 v241, v241
	v_pk_add_f32 v[234:235], v[234:235], 1.0 op_sel_hi:[1,0]
	v_rcp_f32_e32 v234, v234
	v_rcp_f32_e32 v235, v235
	v_pk_add_f32 v[236:237], v[236:237], 1.0 op_sel_hi:[1,0]
	v_rcp_f32_e32 v236, v236
	v_rcp_f32_e32 v237, v237
	v_pk_add_f32 v[238:239], v[238:239], 1.0 op_sel_hi:[1,0]
	v_rcp_f32_e32 v238, v238
	v_rcp_f32_e32 v239, v239
	v_pk_add_f32 v[240:241], v[240:241], 1.0 op_sel_hi:[1,0]
	v_rcp_f32_e32 v240, v240
	v_rcp_f32_e32 v241, v241
	v_cvt_pk_bf16_f32 v134, v238, v239
	v_cvt_pk_bf16_f32 v135, v240, v241
	v_cvt_pk_bf16_f32 v136, v234, v235
	v_cvt_pk_bf16_f32 v137, v236, v237
	global_store_dwordx4 v[160:161], v[134:137], off offset:256 nt
	v_lshl_add_u64 v[160:161], v[160:161], 0, s[98:99]
	v_pk_mul_f32 v[234:235], v[58:59], v[242:243] op_sel_hi:[1,0]
	v_exp_f32_e32 v234, v234
	v_exp_f32_e32 v235, v235
	v_pk_mul_f32 v[236:237], v[60:61], v[242:243] op_sel_hi:[1,0]
	v_exp_f32_e32 v236, v236
	v_exp_f32_e32 v237, v237
	v_pk_mul_f32 v[238:239], v[62:63], v[242:243] op_sel_hi:[1,0]
	v_exp_f32_e32 v238, v238
	v_exp_f32_e32 v239, v239
	v_pk_mul_f32 v[240:241], v[64:65], v[242:243] op_sel_hi:[1,0]
	v_exp_f32_e32 v240, v240
	v_exp_f32_e32 v241, v241
	v_pk_add_f32 v[234:235], v[234:235], 1.0 op_sel_hi:[1,0]
	v_rcp_f32_e32 v234, v234
	v_rcp_f32_e32 v235, v235
	v_pk_add_f32 v[236:237], v[236:237], 1.0 op_sel_hi:[1,0]
	v_rcp_f32_e32 v236, v236
	v_rcp_f32_e32 v237, v237
	v_pk_add_f32 v[238:239], v[238:239], 1.0 op_sel_hi:[1,0]
	v_rcp_f32_e32 v238, v238
	v_rcp_f32_e32 v239, v239
	v_pk_add_f32 v[240:241], v[240:241], 1.0 op_sel_hi:[1,0]
	v_rcp_f32_e32 v240, v240
	v_rcp_f32_e32 v241, v241
	v_cvt_pk_bf16_f32 v62, v238, v239
	v_cvt_pk_bf16_f32 v63, v240, v241
	v_cvt_pk_bf16_f32 v64, v234, v235
	v_cvt_pk_bf16_f32 v65, v236, v237
	global_store_dwordx4 v[160:161], v[62:65], off nt
	v_pk_mul_f32 v[234:235], v[122:123], v[242:243] op_sel_hi:[1,0]
	v_exp_f32_e32 v234, v234
	v_exp_f32_e32 v235, v235
	v_pk_mul_f32 v[236:237], v[124:125], v[242:243] op_sel_hi:[1,0]
	v_exp_f32_e32 v236, v236
	v_exp_f32_e32 v237, v237
	v_pk_mul_f32 v[238:239], v[126:127], v[242:243] op_sel_hi:[1,0]
	v_exp_f32_e32 v238, v238
	v_exp_f32_e32 v239, v239
	v_pk_mul_f32 v[240:241], v[128:129], v[242:243] op_sel_hi:[1,0]
	v_exp_f32_e32 v240, v240
	v_exp_f32_e32 v241, v241
	v_pk_add_f32 v[234:235], v[234:235], 1.0 op_sel_hi:[1,0]
	v_rcp_f32_e32 v234, v234
	v_rcp_f32_e32 v235, v235
	v_pk_add_f32 v[236:237], v[236:237], 1.0 op_sel_hi:[1,0]
	v_rcp_f32_e32 v236, v236
	v_rcp_f32_e32 v237, v237
	v_pk_add_f32 v[238:239], v[238:239], 1.0 op_sel_hi:[1,0]
	v_rcp_f32_e32 v238, v238
	v_rcp_f32_e32 v239, v239
	v_pk_add_f32 v[240:241], v[240:241], 1.0 op_sel_hi:[1,0]
	v_rcp_f32_e32 v240, v240
	v_rcp_f32_e32 v241, v241
	v_cvt_pk_bf16_f32 v126, v238, v239
	v_cvt_pk_bf16_f32 v127, v240, v241
	v_cvt_pk_bf16_f32 v128, v234, v235
	v_cvt_pk_bf16_f32 v129, v236, v237
	global_store_dwordx4 v[160:161], v[126:129], off offset:256 nt
	v_lshl_add_u64 v[160:161], v[160:161], 0, s[98:99]
	v_pk_mul_f32 v[234:235], v[50:51], v[242:243] op_sel_hi:[1,0]
	v_exp_f32_e32 v234, v234
	v_exp_f32_e32 v235, v235
	v_pk_mul_f32 v[236:237], v[52:53], v[242:243] op_sel_hi:[1,0]
	v_exp_f32_e32 v236, v236
	v_exp_f32_e32 v237, v237
	v_pk_mul_f32 v[238:239], v[54:55], v[242:243] op_sel_hi:[1,0]
	v_exp_f32_e32 v238, v238
	v_exp_f32_e32 v239, v239
	v_pk_mul_f32 v[240:241], v[56:57], v[242:243] op_sel_hi:[1,0]
	v_exp_f32_e32 v240, v240
	v_exp_f32_e32 v241, v241
	v_pk_add_f32 v[234:235], v[234:235], 1.0 op_sel_hi:[1,0]
	v_rcp_f32_e32 v234, v234
	v_rcp_f32_e32 v235, v235
	v_pk_add_f32 v[236:237], v[236:237], 1.0 op_sel_hi:[1,0]
	v_rcp_f32_e32 v236, v236
	v_rcp_f32_e32 v237, v237
	v_pk_add_f32 v[238:239], v[238:239], 1.0 op_sel_hi:[1,0]
	v_rcp_f32_e32 v238, v238
	v_rcp_f32_e32 v239, v239
	v_pk_add_f32 v[240:241], v[240:241], 1.0 op_sel_hi:[1,0]
	v_rcp_f32_e32 v240, v240
	v_rcp_f32_e32 v241, v241
	v_cvt_pk_bf16_f32 v54, v238, v239
	v_cvt_pk_bf16_f32 v55, v240, v241
	v_cvt_pk_bf16_f32 v56, v234, v235
	v_cvt_pk_bf16_f32 v57, v236, v237
	global_store_dwordx4 v[160:161], v[54:57], off nt
	v_pk_mul_f32 v[234:235], v[114:115], v[242:243] op_sel_hi:[1,0]
	v_exp_f32_e32 v234, v234
	v_exp_f32_e32 v235, v235
	v_pk_mul_f32 v[236:237], v[116:117], v[242:243] op_sel_hi:[1,0]
	v_exp_f32_e32 v236, v236
	v_exp_f32_e32 v237, v237
	v_pk_mul_f32 v[238:239], v[118:119], v[242:243] op_sel_hi:[1,0]
	v_exp_f32_e32 v238, v238
	v_exp_f32_e32 v239, v239
	v_pk_mul_f32 v[240:241], v[120:121], v[242:243] op_sel_hi:[1,0]
	v_exp_f32_e32 v240, v240
	v_exp_f32_e32 v241, v241
	v_pk_add_f32 v[234:235], v[234:235], 1.0 op_sel_hi:[1,0]
	v_rcp_f32_e32 v234, v234
	v_rcp_f32_e32 v235, v235
	v_pk_add_f32 v[236:237], v[236:237], 1.0 op_sel_hi:[1,0]
	v_rcp_f32_e32 v236, v236
	v_rcp_f32_e32 v237, v237
	v_pk_add_f32 v[238:239], v[238:239], 1.0 op_sel_hi:[1,0]
	v_rcp_f32_e32 v238, v238
	v_rcp_f32_e32 v239, v239
	v_pk_add_f32 v[240:241], v[240:241], 1.0 op_sel_hi:[1,0]
	v_rcp_f32_e32 v240, v240
	v_rcp_f32_e32 v241, v241
	v_cvt_pk_bf16_f32 v118, v238, v239
	v_cvt_pk_bf16_f32 v119, v240, v241
	v_cvt_pk_bf16_f32 v120, v234, v235
	v_cvt_pk_bf16_f32 v121, v236, v237
	global_store_dwordx4 v[160:161], v[118:121], off offset:256 nt
	v_lshl_add_u64 v[160:161], v[160:161], 0, s[98:99]
	v_pk_mul_f32 v[234:235], v[42:43], v[242:243] op_sel_hi:[1,0]
	v_exp_f32_e32 v234, v234
	v_exp_f32_e32 v235, v235
	v_pk_mul_f32 v[236:237], v[44:45], v[242:243] op_sel_hi:[1,0]
	v_exp_f32_e32 v236, v236
	v_exp_f32_e32 v237, v237
	v_pk_mul_f32 v[238:239], v[46:47], v[242:243] op_sel_hi:[1,0]
	v_exp_f32_e32 v238, v238
	v_exp_f32_e32 v239, v239
	v_pk_mul_f32 v[240:241], v[48:49], v[242:243] op_sel_hi:[1,0]
	v_exp_f32_e32 v240, v240
	v_exp_f32_e32 v241, v241
	v_pk_add_f32 v[234:235], v[234:235], 1.0 op_sel_hi:[1,0]
	v_rcp_f32_e32 v234, v234
	v_rcp_f32_e32 v235, v235
	v_pk_add_f32 v[236:237], v[236:237], 1.0 op_sel_hi:[1,0]
	v_rcp_f32_e32 v236, v236
	v_rcp_f32_e32 v237, v237
	v_pk_add_f32 v[238:239], v[238:239], 1.0 op_sel_hi:[1,0]
	v_rcp_f32_e32 v238, v238
	v_rcp_f32_e32 v239, v239
	v_pk_add_f32 v[240:241], v[240:241], 1.0 op_sel_hi:[1,0]
	v_rcp_f32_e32 v240, v240
	v_rcp_f32_e32 v241, v241
	v_cvt_pk_bf16_f32 v46, v238, v239
	v_cvt_pk_bf16_f32 v47, v240, v241
	v_cvt_pk_bf16_f32 v48, v234, v235
	v_cvt_pk_bf16_f32 v49, v236, v237
	global_store_dwordx4 v[160:161], v[46:49], off nt
	v_pk_mul_f32 v[234:235], v[106:107], v[242:243] op_sel_hi:[1,0]
	v_exp_f32_e32 v234, v234
	v_exp_f32_e32 v235, v235
	v_pk_mul_f32 v[236:237], v[108:109], v[242:243] op_sel_hi:[1,0]
	v_exp_f32_e32 v236, v236
	v_exp_f32_e32 v237, v237
	v_pk_mul_f32 v[238:239], v[110:111], v[242:243] op_sel_hi:[1,0]
	v_exp_f32_e32 v238, v238
	v_exp_f32_e32 v239, v239
	v_pk_mul_f32 v[240:241], v[112:113], v[242:243] op_sel_hi:[1,0]
	v_exp_f32_e32 v240, v240
	v_exp_f32_e32 v241, v241
	v_pk_add_f32 v[234:235], v[234:235], 1.0 op_sel_hi:[1,0]
	v_rcp_f32_e32 v234, v234
	v_rcp_f32_e32 v235, v235
	v_pk_add_f32 v[236:237], v[236:237], 1.0 op_sel_hi:[1,0]
	v_rcp_f32_e32 v236, v236
	v_rcp_f32_e32 v237, v237
	v_pk_add_f32 v[238:239], v[238:239], 1.0 op_sel_hi:[1,0]
	v_rcp_f32_e32 v238, v238
	v_rcp_f32_e32 v239, v239
	v_pk_add_f32 v[240:241], v[240:241], 1.0 op_sel_hi:[1,0]
	v_rcp_f32_e32 v240, v240
	v_rcp_f32_e32 v241, v241
	v_cvt_pk_bf16_f32 v110, v238, v239
	v_cvt_pk_bf16_f32 v111, v240, v241
	v_cvt_pk_bf16_f32 v112, v234, v235
	v_cvt_pk_bf16_f32 v113, v236, v237
	global_store_dwordx4 v[160:161], v[110:113], off offset:256 nt
	v_lshl_add_u64 v[160:161], v[160:161], 0, s[100:101]
	v_pk_mul_f32 v[234:235], v[26:27], v[242:243] op_sel_hi:[1,0]
	v_exp_f32_e32 v234, v234
	v_exp_f32_e32 v235, v235
	v_pk_mul_f32 v[236:237], v[28:29], v[242:243] op_sel_hi:[1,0]
	v_exp_f32_e32 v236, v236
	v_exp_f32_e32 v237, v237
	v_pk_mul_f32 v[238:239], v[34:35], v[242:243] op_sel_hi:[1,0]
	v_exp_f32_e32 v238, v238
	v_exp_f32_e32 v239, v239
	v_pk_mul_f32 v[240:241], v[36:37], v[242:243] op_sel_hi:[1,0]
	v_exp_f32_e32 v240, v240
	v_exp_f32_e32 v241, v241
	v_pk_add_f32 v[234:235], v[234:235], 1.0 op_sel_hi:[1,0]
	v_rcp_f32_e32 v234, v234
	v_rcp_f32_e32 v235, v235
	v_pk_add_f32 v[236:237], v[236:237], 1.0 op_sel_hi:[1,0]
	v_rcp_f32_e32 v236, v236
	v_rcp_f32_e32 v237, v237
	v_pk_add_f32 v[238:239], v[238:239], 1.0 op_sel_hi:[1,0]
	v_rcp_f32_e32 v238, v238
	v_rcp_f32_e32 v239, v239
	v_pk_add_f32 v[240:241], v[240:241], 1.0 op_sel_hi:[1,0]
	v_rcp_f32_e32 v240, v240
	v_rcp_f32_e32 v241, v241
	v_cvt_pk_bf16_f32 v34, v238, v239
	v_cvt_pk_bf16_f32 v35, v240, v241
	v_cvt_pk_bf16_f32 v36, v234, v235
	v_cvt_pk_bf16_f32 v37, v236, v237
	global_store_dwordx4 v[160:161], v[34:37], off nt
	v_pk_mul_f32 v[234:235], v[90:91], v[242:243] op_sel_hi:[1,0]
	v_exp_f32_e32 v234, v234
	v_exp_f32_e32 v235, v235
	v_pk_mul_f32 v[236:237], v[92:93], v[242:243] op_sel_hi:[1,0]
	v_exp_f32_e32 v236, v236
	v_exp_f32_e32 v237, v237
	v_pk_mul_f32 v[238:239], v[94:95], v[242:243] op_sel_hi:[1,0]
	v_exp_f32_e32 v238, v238
	v_exp_f32_e32 v239, v239
	v_pk_mul_f32 v[240:241], v[96:97], v[242:243] op_sel_hi:[1,0]
	v_exp_f32_e32 v240, v240
	v_exp_f32_e32 v241, v241
	v_pk_add_f32 v[234:235], v[234:235], 1.0 op_sel_hi:[1,0]
	v_rcp_f32_e32 v234, v234
	v_rcp_f32_e32 v235, v235
	v_pk_add_f32 v[236:237], v[236:237], 1.0 op_sel_hi:[1,0]
	v_rcp_f32_e32 v236, v236
	v_rcp_f32_e32 v237, v237
	v_pk_add_f32 v[238:239], v[238:239], 1.0 op_sel_hi:[1,0]
	v_rcp_f32_e32 v238, v238
	v_rcp_f32_e32 v239, v239
	v_pk_add_f32 v[240:241], v[240:241], 1.0 op_sel_hi:[1,0]
	v_rcp_f32_e32 v240, v240
	v_rcp_f32_e32 v241, v241
	v_cvt_pk_bf16_f32 v94, v238, v239
	v_cvt_pk_bf16_f32 v95, v240, v241
	v_cvt_pk_bf16_f32 v96, v234, v235
	v_cvt_pk_bf16_f32 v97, v236, v237
	global_store_dwordx4 v[160:161], v[94:97], off offset:256 nt
	v_lshl_add_u64 v[160:161], v[160:161], 0, s[98:99]
	v_pk_mul_f32 v[234:235], v[18:19], v[242:243] op_sel_hi:[1,0]
	v_exp_f32_e32 v234, v234
	v_exp_f32_e32 v235, v235
	v_pk_mul_f32 v[236:237], v[20:21], v[242:243] op_sel_hi:[1,0]
	v_exp_f32_e32 v236, v236
	v_exp_f32_e32 v237, v237
	v_pk_mul_f32 v[238:239], v[22:23], v[242:243] op_sel_hi:[1,0]
	v_exp_f32_e32 v238, v238
	v_exp_f32_e32 v239, v239
	v_pk_mul_f32 v[240:241], v[24:25], v[242:243] op_sel_hi:[1,0]
	v_exp_f32_e32 v240, v240
	v_exp_f32_e32 v241, v241
	v_pk_add_f32 v[234:235], v[234:235], 1.0 op_sel_hi:[1,0]
	v_rcp_f32_e32 v234, v234
	v_rcp_f32_e32 v235, v235
	v_pk_add_f32 v[236:237], v[236:237], 1.0 op_sel_hi:[1,0]
	v_rcp_f32_e32 v236, v236
	v_rcp_f32_e32 v237, v237
	v_pk_add_f32 v[238:239], v[238:239], 1.0 op_sel_hi:[1,0]
	v_rcp_f32_e32 v238, v238
	v_rcp_f32_e32 v239, v239
	v_pk_add_f32 v[240:241], v[240:241], 1.0 op_sel_hi:[1,0]
	v_rcp_f32_e32 v240, v240
	v_rcp_f32_e32 v241, v241
	v_cvt_pk_bf16_f32 v22, v238, v239
	v_cvt_pk_bf16_f32 v23, v240, v241
	v_cvt_pk_bf16_f32 v24, v234, v235
	v_cvt_pk_bf16_f32 v25, v236, v237
	global_store_dwordx4 v[160:161], v[22:25], off nt
	v_pk_mul_f32 v[234:235], v[82:83], v[242:243] op_sel_hi:[1,0]
	v_exp_f32_e32 v234, v234
	v_exp_f32_e32 v235, v235
	v_pk_mul_f32 v[236:237], v[84:85], v[242:243] op_sel_hi:[1,0]
	v_exp_f32_e32 v236, v236
	v_exp_f32_e32 v237, v237
	v_pk_mul_f32 v[238:239], v[86:87], v[242:243] op_sel_hi:[1,0]
	v_exp_f32_e32 v238, v238
	v_exp_f32_e32 v239, v239
	v_pk_mul_f32 v[240:241], v[88:89], v[242:243] op_sel_hi:[1,0]
	v_exp_f32_e32 v240, v240
	v_exp_f32_e32 v241, v241
	v_pk_add_f32 v[234:235], v[234:235], 1.0 op_sel_hi:[1,0]
	v_rcp_f32_e32 v234, v234
	v_rcp_f32_e32 v235, v235
	v_pk_add_f32 v[236:237], v[236:237], 1.0 op_sel_hi:[1,0]
	v_rcp_f32_e32 v236, v236
	v_rcp_f32_e32 v237, v237
	v_pk_add_f32 v[238:239], v[238:239], 1.0 op_sel_hi:[1,0]
	v_rcp_f32_e32 v238, v238
	v_rcp_f32_e32 v239, v239
	v_pk_add_f32 v[240:241], v[240:241], 1.0 op_sel_hi:[1,0]
	v_rcp_f32_e32 v240, v240
	v_rcp_f32_e32 v241, v241
	v_cvt_pk_bf16_f32 v86, v238, v239
	v_cvt_pk_bf16_f32 v87, v240, v241
	v_cvt_pk_bf16_f32 v88, v234, v235
	v_cvt_pk_bf16_f32 v89, v236, v237
	global_store_dwordx4 v[160:161], v[86:89], off offset:256 nt
	v_lshl_add_u64 v[160:161], v[160:161], 0, s[98:99]
	v_pk_mul_f32 v[234:235], v[10:11], v[242:243] op_sel_hi:[1,0]
	v_exp_f32_e32 v234, v234
	v_exp_f32_e32 v235, v235
	v_pk_mul_f32 v[236:237], v[12:13], v[242:243] op_sel_hi:[1,0]
	v_exp_f32_e32 v236, v236
	v_exp_f32_e32 v237, v237
	v_pk_mul_f32 v[238:239], v[14:15], v[242:243] op_sel_hi:[1,0]
	v_exp_f32_e32 v238, v238
	v_exp_f32_e32 v239, v239
	v_pk_mul_f32 v[240:241], v[16:17], v[242:243] op_sel_hi:[1,0]
	v_exp_f32_e32 v240, v240
	v_exp_f32_e32 v241, v241
	v_pk_add_f32 v[234:235], v[234:235], 1.0 op_sel_hi:[1,0]
	v_rcp_f32_e32 v234, v234
	v_rcp_f32_e32 v235, v235
	v_pk_add_f32 v[236:237], v[236:237], 1.0 op_sel_hi:[1,0]
	v_rcp_f32_e32 v236, v236
	v_rcp_f32_e32 v237, v237
	v_pk_add_f32 v[238:239], v[238:239], 1.0 op_sel_hi:[1,0]
	v_rcp_f32_e32 v238, v238
	v_rcp_f32_e32 v239, v239
	v_pk_add_f32 v[240:241], v[240:241], 1.0 op_sel_hi:[1,0]
	v_rcp_f32_e32 v240, v240
	v_rcp_f32_e32 v241, v241
	v_cvt_pk_bf16_f32 v14, v238, v239
	v_cvt_pk_bf16_f32 v15, v240, v241
	v_cvt_pk_bf16_f32 v16, v234, v235
	v_cvt_pk_bf16_f32 v17, v236, v237
	global_store_dwordx4 v[160:161], v[14:17], off nt
	v_pk_mul_f32 v[234:235], v[74:75], v[242:243] op_sel_hi:[1,0]
	v_exp_f32_e32 v234, v234
	v_exp_f32_e32 v235, v235
	v_pk_mul_f32 v[236:237], v[76:77], v[242:243] op_sel_hi:[1,0]
	v_exp_f32_e32 v236, v236
	v_exp_f32_e32 v237, v237
	v_pk_mul_f32 v[238:239], v[78:79], v[242:243] op_sel_hi:[1,0]
	v_exp_f32_e32 v238, v238
	v_exp_f32_e32 v239, v239
	v_pk_mul_f32 v[240:241], v[80:81], v[242:243] op_sel_hi:[1,0]
	v_exp_f32_e32 v240, v240
	v_exp_f32_e32 v241, v241
	v_pk_add_f32 v[234:235], v[234:235], 1.0 op_sel_hi:[1,0]
	v_rcp_f32_e32 v234, v234
	v_rcp_f32_e32 v235, v235
	v_pk_add_f32 v[236:237], v[236:237], 1.0 op_sel_hi:[1,0]
	v_rcp_f32_e32 v236, v236
	v_rcp_f32_e32 v237, v237
	v_pk_add_f32 v[238:239], v[238:239], 1.0 op_sel_hi:[1,0]
	v_rcp_f32_e32 v238, v238
	v_rcp_f32_e32 v239, v239
	v_pk_add_f32 v[240:241], v[240:241], 1.0 op_sel_hi:[1,0]
	v_rcp_f32_e32 v240, v240
	v_rcp_f32_e32 v241, v241
	v_cvt_pk_bf16_f32 v78, v238, v239
	v_cvt_pk_bf16_f32 v79, v240, v241
	v_cvt_pk_bf16_f32 v80, v234, v235
	v_cvt_pk_bf16_f32 v81, v236, v237
	global_store_dwordx4 v[160:161], v[78:81], off offset:256 nt
	v_lshl_add_u64 v[160:161], v[160:161], 0, s[98:99]
	v_pk_mul_f32 v[234:235], v[2:3], v[242:243] op_sel_hi:[1,0]
	v_exp_f32_e32 v234, v234
	v_exp_f32_e32 v235, v235
	v_pk_mul_f32 v[236:237], v[4:5], v[242:243] op_sel_hi:[1,0]
	v_exp_f32_e32 v236, v236
	v_exp_f32_e32 v237, v237
	v_pk_mul_f32 v[238:239], v[6:7], v[242:243] op_sel_hi:[1,0]
	v_exp_f32_e32 v238, v238
	v_exp_f32_e32 v239, v239
	v_pk_mul_f32 v[240:241], v[8:9], v[242:243] op_sel_hi:[1,0]
	v_exp_f32_e32 v240, v240
	v_exp_f32_e32 v241, v241
	v_pk_add_f32 v[234:235], v[234:235], 1.0 op_sel_hi:[1,0]
	v_rcp_f32_e32 v234, v234
	v_rcp_f32_e32 v235, v235
	v_pk_add_f32 v[236:237], v[236:237], 1.0 op_sel_hi:[1,0]
	v_rcp_f32_e32 v236, v236
	v_rcp_f32_e32 v237, v237
	v_pk_add_f32 v[238:239], v[238:239], 1.0 op_sel_hi:[1,0]
	v_rcp_f32_e32 v238, v238
	v_rcp_f32_e32 v239, v239
	v_pk_add_f32 v[240:241], v[240:241], 1.0 op_sel_hi:[1,0]
	v_rcp_f32_e32 v240, v240
	v_rcp_f32_e32 v241, v241
	v_cvt_pk_bf16_f32 v6, v238, v239
	v_cvt_pk_bf16_f32 v7, v240, v241
	v_cvt_pk_bf16_f32 v8, v234, v235
	v_cvt_pk_bf16_f32 v9, v236, v237
	global_store_dwordx4 v[160:161], v[6:9], off nt
	v_pk_mul_f32 v[234:235], v[30:31], v[242:243] op_sel_hi:[1,0]
	v_exp_f32_e32 v234, v234
	v_exp_f32_e32 v235, v235
	v_pk_mul_f32 v[236:237], v[32:33], v[242:243] op_sel_hi:[1,0]
	v_exp_f32_e32 v236, v236
	v_exp_f32_e32 v237, v237
	v_pk_mul_f32 v[238:239], v[38:39], v[242:243] op_sel_hi:[1,0]
	v_exp_f32_e32 v238, v238
	v_exp_f32_e32 v239, v239
	v_pk_mul_f32 v[240:241], v[40:41], v[242:243] op_sel_hi:[1,0]
	v_exp_f32_e32 v240, v240
	v_exp_f32_e32 v241, v241
	v_pk_add_f32 v[234:235], v[234:235], 1.0 op_sel_hi:[1,0]
	v_rcp_f32_e32 v234, v234
	v_rcp_f32_e32 v235, v235
	v_pk_add_f32 v[236:237], v[236:237], 1.0 op_sel_hi:[1,0]
	v_rcp_f32_e32 v236, v236
	v_rcp_f32_e32 v237, v237
	v_pk_add_f32 v[238:239], v[238:239], 1.0 op_sel_hi:[1,0]
	v_rcp_f32_e32 v238, v238
	v_rcp_f32_e32 v239, v239
	v_pk_add_f32 v[240:241], v[240:241], 1.0 op_sel_hi:[1,0]
	v_rcp_f32_e32 v240, v240
	v_rcp_f32_e32 v241, v241
	v_cvt_pk_bf16_f32 v38, v238, v239
	v_cvt_pk_bf16_f32 v39, v240, v241
	v_cvt_pk_bf16_f32 v40, v234, v235
	v_cvt_pk_bf16_f32 v41, v236, v237
	global_store_dwordx4 v[160:161], v[38:41], off offset:256 nt
	s_branch .Lepn1_dn
.Lepn1_m0:
	v_lshl_or_b32 v158, s4, 8, v167
	v_mov_b64_e32 v[160:161], s[64:65]
	v_ashrrev_i32_e32 v159, 31, v158
	v_mad_i64_i32 v[160:161], s[4:5], v156, s49, v[160:161]
	v_lshl_add_u64 v[160:161], v[158:159], 1, v[160:161]
	s_lshl_b32 s98, s49, 4
	s_mov_b32 s99, 0
	s_mul_i32 s100, s49, 0x50
	s_mov_b32 s101, 0
	v_cvt_pk_bf16_f32 v70, v70, v71
	v_cvt_pk_bf16_f32 v71, v72, v73
	v_cvt_pk_bf16_f32 v72, v66, v67
	v_cvt_pk_bf16_f32 v73, v68, v69
	global_store_dwordx4 v[160:161], v[70:73], off nt
	v_cvt_pk_bf16_f32 v134, v134, v135
	v_cvt_pk_bf16_f32 v135, v136, v137
	v_cvt_pk_bf16_f32 v136, v130, v131
	v_cvt_pk_bf16_f32 v137, v132, v133
	global_store_dwordx4 v[160:161], v[134:137], off offset:256 nt
	v_lshl_add_u64 v[160:161], v[160:161], 0, s[98:99]
	v_cvt_pk_bf16_f32 v62, v62, v63
	v_cvt_pk_bf16_f32 v63, v64, v65
	v_cvt_pk_bf16_f32 v64, v58, v59
	v_cvt_pk_bf16_f32 v65, v60, v61
	global_store_dwordx4 v[160:161], v[62:65], off nt
	v_cvt_pk_bf16_f32 v126, v126, v127
	v_cvt_pk_bf16_f32 v127, v128, v129
	v_cvt_pk_bf16_f32 v128, v122, v123
	v_cvt_pk_bf16_f32 v129, v124, v125
	global_store_dwordx4 v[160:161], v[126:129], off offset:256 nt
	v_lshl_add_u64 v[160:161], v[160:161], 0, s[98:99]
	v_cvt_pk_bf16_f32 v54, v54, v55
	v_cvt_pk_bf16_f32 v55, v56, v57
	v_cvt_pk_bf16_f32 v56, v50, v51
	v_cvt_pk_bf16_f32 v57, v52, v53
	global_store_dwordx4 v[160:161], v[54:57], off nt
	v_cvt_pk_bf16_f32 v118, v118, v119
	v_cvt_pk_bf16_f32 v119, v120, v121
	v_cvt_pk_bf16_f32 v120, v114, v115
	v_cvt_pk_bf16_f32 v121, v116, v117
	global_store_dwordx4 v[160:161], v[118:121], off offset:256 nt
	v_lshl_add_u64 v[160:161], v[160:161], 0, s[98:99]
	v_cvt_pk_bf16_f32 v46, v46, v47
	v_cvt_pk_bf16_f32 v47, v48, v49
	v_cvt_pk_bf16_f32 v48, v42, v43
	v_cvt_pk_bf16_f32 v49, v44, v45
	global_store_dwordx4 v[160:161], v[46:49], off nt
	v_cvt_pk_bf16_f32 v110, v110, v111
	v_cvt_pk_bf16_f32 v111, v112, v113
	v_cvt_pk_bf16_f32 v112, v106, v107
	v_cvt_pk_bf16_f32 v113, v108, v109
	global_store_dwordx4 v[160:161], v[110:113], off offset:256 nt
	v_lshl_add_u64 v[160:161], v[160:161], 0, s[100:101]
	v_cvt_pk_bf16_f32 v34, v34, v35
	v_cvt_pk_bf16_f32 v35, v36, v37
	v_cvt_pk_bf16_f32 v36, v26, v27
	v_cvt_pk_bf16_f32 v37, v28, v29
	global_store_dwordx4 v[160:161], v[34:37], off nt
	v_cvt_pk_bf16_f32 v94, v94, v95
	v_cvt_pk_bf16_f32 v95, v96, v97
	v_cvt_pk_bf16_f32 v96, v90, v91
	v_cvt_pk_bf16_f32 v97, v92, v93
	global_store_dwordx4 v[160:161], v[94:97], off offset:256 nt
	v_lshl_add_u64 v[160:161], v[160:161], 0, s[98:99]
	v_cvt_pk_bf16_f32 v22, v22, v23
	v_cvt_pk_bf16_f32 v23, v24, v25
	v_cvt_pk_bf16_f32 v24, v18, v19
	v_cvt_pk_bf16_f32 v25, v20, v21
	global_store_dwordx4 v[160:161], v[22:25], off nt
	v_cvt_pk_bf16_f32 v86, v86, v87
	v_cvt_pk_bf16_f32 v87, v88, v89
	v_cvt_pk_bf16_f32 v88, v82, v83
	v_cvt_pk_bf16_f32 v89, v84, v85
	global_store_dwordx4 v[160:161], v[86:89], off offset:256 nt
	v_lshl_add_u64 v[160:161], v[160:161], 0, s[98:99]
	v_cvt_pk_bf16_f32 v14, v14, v15
	v_cvt_pk_bf16_f32 v15, v16, v17
	v_cvt_pk_bf16_f32 v16, v10, v11
	v_cvt_pk_bf16_f32 v17, v12, v13
	global_store_dwordx4 v[160:161], v[14:17], off nt
	v_cvt_pk_bf16_f32 v78, v78, v79
	v_cvt_pk_bf16_f32 v79, v80, v81
	v_cvt_pk_bf16_f32 v80, v74, v75
	v_cvt_pk_bf16_f32 v81, v76, v77
	global_store_dwordx4 v[160:161], v[78:81], off offset:256 nt
	v_lshl_add_u64 v[160:161], v[160:161], 0, s[98:99]
	v_cvt_pk_bf16_f32 v6, v6, v7
	v_cvt_pk_bf16_f32 v7, v8, v9
	v_cvt_pk_bf16_f32 v8, v2, v3
	v_cvt_pk_bf16_f32 v9, v4, v5
	global_store_dwordx4 v[160:161], v[6:9], off nt
	v_cvt_pk_bf16_f32 v38, v38, v39
	v_cvt_pk_bf16_f32 v39, v40, v41
	v_cvt_pk_bf16_f32 v40, v30, v31
	v_cvt_pk_bf16_f32 v41, v32, v33
	global_store_dwordx4 v[160:161], v[38:41], off offset:256 nt
.Lepn1_dn:
	s_branch .LBB0_753
.LBB0_751:
	s_andn2_b64 vcc, exec, s[12:13]
	s_cbranch_vccnz .LBB0_753
	v_or_b32_e32 v32, 16, v156
	v_ashrrev_i32_e32 v157, 31, v156
	v_ashrrev_i32_e32 v33, 31, v32
	v_lshlrev_b64 v[30:31], 8, v[156:157]
	v_lshlrev_b64 v[32:33], 8, v[32:33]
	v_lshl_add_u64 v[30:31], v[148:149], 0, v[30:31]
	v_lshl_add_u64 v[32:33], v[148:149], 0, v[32:33]
	global_store_dwordx4 v[30:31], v[70:73], off
	global_store_dwordx4 v[30:31], v[66:69], off offset:16
	global_store_dwordx4 v[32:33], v[62:65], off
	global_store_dwordx4 v[32:33], v[58:61], off offset:16
	v_or_b32_e32 v32, 32, v156
	v_ashrrev_i32_e32 v33, 31, v32
	v_lshlrev_b64 v[32:33], 8, v[32:33]
	v_lshl_add_u64 v[32:33], v[148:149], 0, v[32:33]
	global_store_dwordx4 v[32:33], v[54:57], off
	global_store_dwordx4 v[32:33], v[50:53], off offset:16
	v_or_b32_e32 v32, 48, v156
	v_ashrrev_i32_e32 v33, 31, v32
	s_mov_b32 s0, 0x8000
	v_lshlrev_b64 v[32:33], 8, v[32:33]
	v_add_co_u32_e32 v38, vcc, s0, v30
	v_lshl_add_u64 v[32:33], v[148:149], 0, v[32:33]
	s_mov_b64 s[4:5], 0x8000
	v_addc_co_u32_e32 v39, vcc, 0, v31, vcc
	global_store_dwordx4 v[32:33], v[46:49], off
	global_store_dwordx4 v[32:33], v[42:45], off offset:16
	v_lshl_add_u64 v[32:33], v[30:31], 0, s[4:5]
	global_store_dwordx4 v[38:39], v[34:37], off
	global_store_dwordx4 v[32:33], v[26:29], off offset:16
	s_mov_b64 s[4:5], 0x9000
	s_nop 0
	v_add_co_u32_e32 v28, vcc, 0x9000, v30
	v_lshl_add_u64 v[26:27], v[30:31], 0, s[4:5]
	s_nop 0
	v_addc_co_u32_e32 v29, vcc, 0, v31, vcc
	global_store_dwordx4 v[28:29], v[22:25], off
	global_store_dwordx4 v[26:27], v[18:21], off offset:16
	s_nop 1
	v_add_co_u32_e32 v20, vcc, 0xa000, v30
	v_lshl_add_u64 v[18:19], v[30:31], 0, s[14:15]
	s_nop 0
	v_addc_co_u32_e32 v21, vcc, 0, v31, vcc
	global_store_dwordx4 v[20:21], v[14:17], off
	global_store_dwordx4 v[18:19], v[10:13], off offset:16
	s_nop 1
	v_add_co_u32_e32 v12, vcc, 0xb000, v30
	v_lshl_add_u64 v[10:11], v[30:31], 0, s[16:17]
	s_nop 0
	v_addc_co_u32_e32 v13, vcc, 0, v31, vcc
	global_store_dwordx4 v[12:13], v[6:9], off
	global_store_dwordx4 v[10:11], v[2:5], off offset:16
